# v17: attention KV loop with a third V tile buffer in spare LDS (tile t -> buffer t mod 3), loop unrolled x3, the pre-write s_barrier of each half removed (one barrier per KV tile)
# speedup vs baseline: 1.0327x; 1.0061x over previous
; #define LAS __attribute__((address_space(3)))
; __device__ __forceinline__ int opaque_tid(int wv) { return wv * 64 + opaque_lane(); }
; __device__ __forceinline__ int v_st(int k, int c) { const int kk = (k & ~0xC) | ((k & 4) << 1) | ((k & 8) >> 1); return ((kk >> 3) * 4 + (c >> 5)) * 512 + ((kk & 7) * 32 + (c & 31)) * 2; }
; __device__ __forceinline__ int v_rd_base(int lane) { return ((lane & 3) << 3) | (((lane >> 2) & 3) << 6) | (((lane >> 4) & 1) << 5) | (((lane >> 5) & 1) << 8); }
; #define SWRITE(b) do { *(bf16x8*)(V_lds + (b) * SHM_V + vst0) = vs0; *(bf16x8*)(V_lds + (b) * SHM_V + vst1) = vs1; const int kc = sc * 2; \
;     *(bf16x8*)(K_lds + (b) * SHM_K + KSWZ(sr, kc)) = ks0; *(bf16x8*)(K_lds + (b) * SHM_K + KSWZ(32 + sr, kc)) = ks1; \
;     *(bf16x8*)(R_lds + (b) * SHM_R + RSWZ(rr, rc * 2)) = rs0; } while (0)
; #define SWAIT() asm volatile("s_waitcnt vmcnt(0)" ::: "memory")
; __device__ __forceinline__ void attn_body(const bf16_t* __restrict__ Qb, const bf16_t* __restrict__ Kh, const bf16_t* __restrict__ Vh, const bf16_t* __restrict__ Rh,
;                                           bf16_t* __restrict__ Zb, int seq, char* lds, int wv, bool nowrite) {
;     const int tid = opaque_tid(wv), wid = wv, lane = tid & 63, r32 = lane & 31, hi = lane >> 5;
;     char* V_lds = lds + OFF_V; char* K_lds = lds + OFF_K; char* R_lds = lds + OFF_R;
;     float* ws = (float*)(lds + OFF_WS) + wid * 64; float* li_l = ws; float* al_l = ws + 32;
;     float m_reg = -1e30f, l_reg = 0; f32x16 o[4] = {}; bf16x8 qr[8];
;     const bf16_t* Qw = Qb + (long)(wid * QBLK + r32) * LDQ + hi * 8;
;     char* Qp = lds + OFF_QR + wid * 4096;
; #pragma unroll
;     for (int d0 = 0; d0 < 8; ++d0) qr[d0] = *reinterpret_cast<const bf16x8*>(Qw + d0 * 16);
; #pragma unroll
;     for (int d0 = 0; d0 < 4; ++d0) *reinterpret_cast<bf16x8*>(Qp + RSWZ(r32, (d0 * 16 + hi * 8) * 2)) = *reinterpret_cast<const bf16x8*>(Qw + 128 + d0 * 16);
;     const int sr = tid >> 4, sc = (tid & 15) * 8, vst0 = v_st(sr, sc), vst1 = v_st(32 + sr, sc);
;     const int rr = tid >> 3, rc = (tid & 7) * 8;
;     const int vb0 = (int)(uintptr_t)(LAS char*)V_lds + v_rd_base(lane);
;     bf16x8 vs0, vs1, ks0, ks1, rs0;
;     ...
;     f32x16 pA0, pA1, pB0, pB1; float mnA, mnB, alA, alB; bf16x8 pa0, pa1, pa2, pa3; const int NT = seq / KVBLK;
;     SLOAD(0); SWAIT(); SWRITE(0); __syncthreads();
.LBB0_607:
	s_ashr_i32 s56, s3, 4
	s_ashr_i32 s57, s56, 31
	s_and_b32 s8, s3, 15
	s_lshl_b64 s[6:7], s[56:57], 11
	s_add_u32 s42, s6, s68
	s_addc_u32 s43, s7, 0
	s_lshl_b32 s2, s2, 8
	s_and_b32 s24, s2, 0x700
	s_or_b32 s2, s6, s24
	s_mul_i32 s3, s7, 0x1800
	s_mul_hi_u32 s6, s2, 0x1800
	s_add_i32 s6, s6, s3
	s_mulk_i32 s2, 0x1800
	s_add_u32 s2, s35, s2
	s_addc_u32 s3, s50, s6
	s_mul_i32 s6, s8, 0x180
	s_add_u32 s2, s2, s6
	v_mov_b32_e32 v57, v233
	s_addc_u32 s3, s3, 0
	v_mov_b64_e32 v[0:1], s[2:3]
	v_and_b32_e32 v164, 31, v57
	v_bfe_u32 v165, v57, 5, 1
	v_or_b32_e32 v2, s52, v164
	v_mad_u64_u32 v[0:1], s[2:3], v2, s85, v[0:1]
	v_lshlrev_b32_e32 v212, 4, v165
	v_lshl_add_u64 v[36:37], v[0:1], 0, v[212:213]
	global_load_dwordx4 v[0:3], v[36:37], off offset:256
	global_load_dwordx4 v[4:7], v[36:37], off offset:288
	global_load_dwordx4 v[8:11], v[36:37], off offset:320
	global_load_dwordx4 v[12:15], v[36:37], off offset:352
	s_lshl_b64 s[60:61], s[56:57], 23
	s_add_u32 s6, s51, s60
	s_addc_u32 s7, s64, s61
	s_lshl_b32 s2, s8, 7
	s_lshl_b32 s3, s8, 8
	s_add_u32 s6, s6, s3
	s_addc_u32 s7, s7, 0
	s_add_u32 s8, s65, s60
	v_add_u32_e32 v56, s75, v57
	s_addc_u32 s9, s70, s61
	v_ashrrev_i32_e32 v38, 4, v56
	s_add_u32 s62, s8, s3
	v_lshlrev_b32_e32 v46, 3, v56
	v_add_u32_e32 v40, 32, v38
	s_addc_u32 s63, s9, 0
	s_lshl_b64 s[8:9], s[42:43], 7
	v_and_b32_e32 v16, 0x78, v46
	v_ashrrev_i32_e32 v39, 31, v38
	v_ashrrev_i32_e32 v41, 31, v40
	v_ashrrev_i32_e32 v42, 3, v56
	s_add_u32 s8, s71, s8
	v_lshlrev_b32_e32 v47, 1, v16
	v_lshlrev_b64 v[48:49], 12, v[38:39]
	v_lshlrev_b64 v[24:25], 12, v[40:41]
	v_ashrrev_i32_e32 v43, 31, v42
	v_or_b32_e32 v52, v48, v47
	v_mov_b32_e32 v53, v49
	v_or_b32_e32 v24, v24, v47
	s_addc_u32 s9, s76, s9
	v_lshlrev_b64 v[50:51], 7, v[42:43]
	v_lshlrev_b32_e32 v75, 4, v56
	v_lshl_add_u64 v[16:17], s[62:63], 0, v[52:53]
	v_lshl_add_u64 v[20:21], s[62:63], 0, v[24:25]
	v_lshl_add_u64 v[26:27], s[6:7], 0, v[52:53]
	v_lshl_add_u64 v[28:29], s[6:7], 0, v[24:25]
	v_lshl_add_u64 v[32:33], s[8:9], 0, v[50:51]
	v_and_b32_e32 v44, 0x70, v75
	v_mov_b32_e32 v45, v213
	global_load_dwordx4 v[16:19], v[16:17], off
	v_lshl_add_u64 v[54:55], v[32:33], 0, v[44:45]
	global_load_dwordx4 v[20:23], v[20:21], off
	s_nop 0
	global_load_dwordx4 v[24:27], v[26:27], off
	s_nop 0
	global_load_dwordx4 v[28:31], v[28:29], off
	s_nop 0
	global_load_dwordx4 v[32:35], v[54:55], off
	global_load_dwordx4 v[120:123], v[36:37], off
	global_load_dwordx4 v[124:127], v[36:37], off offset:32
	global_load_dwordx4 v[116:119], v[36:37], off offset:64
	global_load_dwordx4 v[112:115], v[36:37], off offset:96
	global_load_dwordx4 v[108:111], v[36:37], off offset:128
	global_load_dwordx4 v[104:107], v[36:37], off offset:160
	global_load_dwordx4 v[100:103], v[36:37], off offset:192
	global_load_dwordx4 v[96:99], v[36:37], off offset:224
	v_lshlrev_b32_e32 v39, 3, v57
	v_lshlrev_b32_e32 v58, 7, v164
	v_and_b32_e32 v59, 0x70, v39
	v_add_u32_e32 v41, s96, v58
	v_bitop3_b32 v39, v212, v39, s66 bitop3:0x78
	v_bitop3_b32 v43, v212, v59, 32 bitop3:0x36
	v_bitop3_b32 v45, v212, v59, 64 bitop3:0x36
	v_add_u32_e32 v39, v41, v39
	v_add_u32_e32 v43, v41, v43
	v_add_u32_e32 v45, v41, v45
	v_lshlrev_b32_e32 v60, 4, v57
	s_add_i32 s8, 0, 0x10000
	v_or_b32_e32 v61, 64, v212
	v_or_b32_e32 v62, 0x60, v212
	v_bitop3_b32 v186, v212, v58, v59 bitop3:0xde
	v_add_u32_e32 v187, s8, v186
	v_add_u32_e32 v177, s96, v186
	v_and_b32_e32 v77, 63, v57
	v_bitop3_b32 v190, v61, v58, v59 bitop3:0xde
	v_add_u32_e32 v191, s8, v190
	v_add_u32_e32 v178, s96, v190
	v_bitop3_b32 v192, v62, v58, v59 bitop3:0xde
	s_waitcnt vmcnt(0)
	ds_write_b128 v39, v[0:3]
	ds_write_b128 v43, v[4:7]
	ds_write_b128 v45, v[8:11]
	v_bitop3_b32 v0, v212, v59, s31 bitop3:0x36
	v_add_u32_e32 v0, v41, v0
	ds_write_b128 v0, v[12:15]
	v_and_b32_e32 v0, 0xfffff0, v38
	v_lshlrev_b32_e32 v1, 1, v38
	v_and_b32_e32 v4, 0xfffff0, v40
	v_lshlrev_b32_e32 v5, 1, v40
	v_and_or_b32 v0, v1, 8, v0
	v_and_or_b32 v4, v5, 8, v4
	v_lshrrev_b32_e32 v1, 1, v38
	v_lshrrev_b32_e32 v0, 1, v0
	v_bfe_u32 v2, v46, 5, 2
	v_and_b32_e32 v3, 3, v38
	v_lshrrev_b32_e32 v4, 1, v4
	v_or_b32_e32 v0, v0, v2
	v_and_or_b32 v1, v1, 4, v3
	v_or_b32_e32 v2, v4, v2
	v_lshlrev_b32_e32 v0, 9, v0
	v_lshlrev_b32_e32 v1, 6, v1
	v_and_b32_e32 v3, 48, v47
	v_lshlrev_b32_e32 v2, 9, v2
	v_or3_b32 v0, v0, v1, v3
	v_or3_b32 v1, v2, v1, v3
	v_add_u32_e32 v170, 0, v0
	v_add_u32_e32 v171, 0, v1
	v_lshlrev_b32_e32 v0, 8, v38
	v_and_b32_e32 v1, 0x70, v56
	v_bitop3_b32 v0, v47, v0, v1 bitop3:0xde
	v_add_u32_e32 v172, 0, v0
	v_lshlrev_b32_e32 v0, 8, v40
	v_bitop3_b32 v0, v47, v0, v1 bitop3:0xde
	v_add_u32_e32 v173, 0, v0
	v_lshlrev_b32_e32 v0, 7, v42
	v_bitop3_b32 v76, v44, v0, v1 bitop3:0xde
	v_add_u32_e32 v0, s8, v76
	v_lshlrev_b32_e32 v8, 8, v164
	v_and_b32_e32 v9, 0x70, v60
	s_waitcnt vmcnt(0)
	v_or_b32_e32 v12, 32, v212
	ds_write_b128 v170, v[16:19]
	v_bitop3_b32 v188, v12, v58, v59 bitop3:0xde
	ds_write_b128 v171, v[20:23]
	ds_write_b128 v172, v[24:27] offset:32768
	ds_write_b128 v173, v[28:31] offset:32768
	ds_write_b128 v0, v[32:35]
	v_bitop3_b32 v0, v212, v8, v9 bitop3:0xde
	v_add_u32_e32 v174, 0, v0
	s_waitcnt lgkmcnt(0)
	s_barrier
; __device__ __forceinline__ void qkt(f32x16& p0, f32x16& p1, const char* Ks, const char* Rs, const bf16x8* qr, const char* Qp, int r32, int hi) {
;     p0 = f32x16{}; p1 = f32x16{};
; #pragma unroll
;     for (int d0 = 0; d0 < 8; ++d0) { const int cb = (d0 * 16 + hi * 8) * 2;
;         const bf16x8 b0 = *reinterpret_cast<const bf16x8*>(Ks + KSWZ(r32, cb));
;         const bf16x8 b1 = *reinterpret_cast<const bf16x8*>(Ks + KSWZ(32 + r32, cb));
;         p0 = __builtin_amdgcn_mfma_f32_32x32x16_bf16(b0, qr[d0], p0, 0, 0, 0);
;         p1 = __builtin_amdgcn_mfma_f32_32x32x16_bf16(b1, qr[d0], p1, 0, 0, 0); }
; #pragma unroll
;     for (int d0 = 0; d0 < 4; ++d0) { const int cb = (d0 * 16 + hi * 8) * 2;
;         const bf16x8 b0 = *reinterpret_cast<const bf16x8*>(Rs + RSWZ(r32, cb));
;         const bf16x8 b1 = *reinterpret_cast<const bf16x8*>(Rs + RSWZ(32 + r32, cb));
;         const bf16x8 qq = *reinterpret_cast<const bf16x8*>(Qp + RSWZ(r32, cb));
;         p0 = __builtin_amdgcn_mfma_f32_32x32x16_bf16(b0, qq, p0, 0, 0, 0);
;         p1 = __builtin_amdgcn_mfma_f32_32x32x16_bf16(b1, qq, p1, 0, 0, 0); }
; }
	ds_read_b128 v[0:3], v174 offset:32768
	ds_read_b128 v[4:7], v174 offset:40960
	s_waitcnt lgkmcnt(1)
	v_mfma_f32_32x32x16_bf16 v[32:47], v[0:3], v[120:123], 0
	v_bitop3_b32 v0, v12, v8, v9 bitop3:0xde
	v_add_u32_e32 v180, 0, v0
	v_add_u32_e32 v189, s8, v188
	v_add_u32_e32 v175, s96, v188
	v_add_u32_e32 v193, s8, v192
	v_add_u32_e32 v176, s96, v192
	s_mov_b32 s8, s25
	s_waitcnt lgkmcnt(0)
	v_mfma_f32_32x32x16_bf16 v[16:31], v[4:7], v[120:123], 0
	ds_read_b128 v[0:3], v180 offset:32768
	ds_read_b128 v[4:7], v180 offset:40960
	s_mov_b32 s9, s25
	s_mov_b32 s10, s25
	s_mov_b32 s11, s25
	s_mov_b32 s12, s25
	s_mov_b32 s13, s25
	s_mov_b32 s14, s25
	s_waitcnt lgkmcnt(1)
	v_mfma_f32_32x32x16_bf16 v[32:47], v[0:3], v[124:127], v[32:47]
	v_bitop3_b32 v0, v61, v8, v9 bitop3:0xde
	v_add_u32_e32 v182, 0, v0
	s_mov_b32 s15, s25
	s_mov_b32 s16, s25
	s_mov_b32 s17, s25
	s_mov_b32 s18, s25
	s_mov_b32 s19, s25
	s_waitcnt lgkmcnt(0)
	v_mfma_f32_32x32x16_bf16 v[16:31], v[4:7], v[124:127], v[16:31]
	ds_read_b128 v[0:3], v182 offset:32768
	ds_read_b128 v[4:7], v182 offset:40960
	s_mov_b32 s20, s25
	s_mov_b32 s21, s25
	s_mov_b32 s22, s25
	s_mov_b32 s23, s25
	v_add_u32_e32 v195, 0, v76
	v_add_u32_e32 v196, 0x12000, v195
	s_waitcnt lgkmcnt(1)
	v_mfma_f32_32x32x16_bf16 v[32:47], v[0:3], v[116:119], v[32:47]
	v_bitop3_b32 v0, v62, v8, v9 bitop3:0xde
	v_add_u32_e32 v184, 0, v0
	v_lshl_add_u64 v[158:159], s[60:61], 0, v[48:49]
	v_lshl_add_u32 v166, v164, 2, s1
	v_mov_b32_e32 v167, 0
	s_waitcnt lgkmcnt(0)
	v_mfma_f32_32x32x16_bf16 v[16:31], v[4:7], v[116:119], v[16:31]
	ds_read_b128 v[0:3], v184 offset:32768
	ds_read_b128 v[4:7], v184 offset:40960
	s_waitcnt lgkmcnt(1)
	v_mfma_f32_32x32x16_bf16 v[32:47], v[0:3], v[112:115], v[32:47]
	v_or_b32_e32 v0, 0x80, v212
	v_bitop3_b32 v0, v0, v8, v9 bitop3:0xde
	v_add_u32_e32 v185, 0, v0
	s_waitcnt lgkmcnt(0)
	v_mfma_f32_32x32x16_bf16 v[16:31], v[4:7], v[112:115], v[16:31]
	ds_read_b128 v[0:3], v185 offset:32768
	ds_read_b128 v[4:7], v185 offset:40960
	s_waitcnt lgkmcnt(1)
	v_mfma_f32_32x32x16_bf16 v[32:47], v[0:3], v[108:111], v[32:47]
	v_or_b32_e32 v0, 0xa0, v212
	v_bitop3_b32 v0, v0, v8, v9 bitop3:0xde
	v_add_u32_e32 v183, 0, v0
	s_waitcnt lgkmcnt(0)
	v_mfma_f32_32x32x16_bf16 v[16:31], v[4:7], v[108:111], v[16:31]
	ds_read_b128 v[0:3], v183 offset:32768
	ds_read_b128 v[4:7], v183 offset:40960
	s_waitcnt lgkmcnt(1)
	v_mfma_f32_32x32x16_bf16 v[32:47], v[0:3], v[104:107], v[32:47]
	v_or_b32_e32 v0, 0xc0, v212
	v_bitop3_b32 v0, v0, v8, v9 bitop3:0xde
	v_add_u32_e32 v181, 0, v0
	s_waitcnt lgkmcnt(0)
	v_mfma_f32_32x32x16_bf16 v[16:31], v[4:7], v[104:107], v[16:31]
	ds_read_b128 v[0:3], v181 offset:32768
	ds_read_b128 v[4:7], v181 offset:40960
	s_waitcnt lgkmcnt(1)
	v_mfma_f32_32x32x16_bf16 v[32:47], v[0:3], v[100:103], v[32:47]
	v_or_b32_e32 v0, 0xe0, v212
	v_bitop3_b32 v0, v0, v8, v9 bitop3:0xde
	v_add_u32_e32 v179, 0, v0
	s_waitcnt lgkmcnt(0)
	v_mfma_f32_32x32x16_bf16 v[16:31], v[4:7], v[100:103], v[16:31]
	ds_read_b128 v[0:3], v179 offset:32768
	ds_read_b128 v[4:7], v179 offset:40960
	s_waitcnt lgkmcnt(1)
	v_mfma_f32_32x32x16_bf16 v[32:47], v[0:3], v[96:99], v[32:47]
	ds_read_b128 v[0:3], v187
	s_waitcnt lgkmcnt(1)
	v_mfma_f32_32x32x16_bf16 v[16:31], v[4:7], v[96:99], v[16:31]
	ds_read_b128 v[4:7], v177
	ds_read_b128 v[8:11], v187 offset:4096
	ds_read_b128 v[12:15], v189
	s_waitcnt lgkmcnt(2)
	v_mfma_f32_32x32x16_bf16 v[32:47], v[0:3], v[4:7], v[32:47]
	s_waitcnt lgkmcnt(1)
	v_mfma_f32_32x32x16_bf16 v[16:31], v[8:11], v[4:7], v[16:31]
	ds_read_b128 v[0:3], v175
	ds_read_b128 v[4:7], v189 offset:4096
	v_lshlrev_b32_e32 v8, 3, v77
	v_and_b32_e32 v9, 0xc0, v60
	s_waitcnt lgkmcnt(1)
	v_mfma_f32_32x32x16_bf16 v[32:47], v[12:15], v[0:3], v[32:47]
	v_and_or_b32 v12, v8, 24, v9
	v_lshlrev_b32_e32 v9, 1, v57
	v_and_b32_e32 v13, 32, v9
	v_and_b32_e32 v14, 0x100, v8
	ds_read_b128 v[8:11], v191
	v_or3_b32 v57, v12, v13, v14
	v_add_u32_e32 v169, 0, v57
	s_waitcnt lgkmcnt(1)
	v_mfma_f32_32x32x16_bf16 v[16:31], v[4:7], v[0:3], v[16:31]
	ds_read_b128 v[0:3], v178
	ds_read_b128 v[4:7], v191 offset:4096
	ds_read_b128 v[12:15], v193
	ds_read_b128 v[58:61], v193 offset:4096
	ds_read_b128 v[62:65], v176
	s_waitcnt lgkmcnt(4)
	v_mfma_f32_32x32x16_bf16 v[32:47], v[8:11], v[0:3], v[32:47]
	s_waitcnt lgkmcnt(3)
	v_mfma_f32_32x32x16_bf16 v[16:31], v[4:7], v[0:3], v[16:31]
	s_waitcnt lgkmcnt(0)
; #define SWRITE(b) do { *(bf16x8*)(V_lds + (b) * SHM_V + vst0) = vs0; *(bf16x8*)(V_lds + (b) * SHM_V + vst1) = vs1; const int kc = sc * 2; \
;     *(bf16x8*)(K_lds + (b) * SHM_K + KSWZ(sr, kc)) = ks0; *(bf16x8*)(K_lds + (b) * SHM_K + KSWZ(32 + sr, kc)) = ks1; \
;     *(bf16x8*)(R_lds + (b) * SHM_R + RSWZ(rr, rc * 2)) = rs0; } while (0)
; #define SWAIT() asm volatile("s_waitcnt vmcnt(0)" ::: "memory")
; __device__ __forceinline__ void partialSM(f32x16& p0, f32x16& p1, float& m_reg, float& mn, float& alpha) {
;     constexpr float C = SCALE * 1.4426950408889634f;
;     float pmax = p0[0];
; #pragma unroll
;     for (int r = 1; r < 16; ++r) pmax = fmaxf(pmax, p0[r]);
; #pragma unroll
;     for (int r = 0; r < 16; ++r) pmax = fmaxf(pmax, p1[r]);
;     { auto rr = __builtin_amdgcn_permlane32_swap(__float_as_uint(pmax), __float_as_uint(pmax), false, false);
;       pmax = fmaxf(__uint_as_float(rr[0]), __uint_as_float(rr[1])); }
;     if (__builtin_expect(__all(pmax - m_reg <= THR / SCALE), 1)) { mn = m_reg; alpha = 1.f; }
;     else { mn = fmaxf(m_reg, pmax); alpha = __builtin_amdgcn_exp2f((m_reg - mn) * C); m_reg = mn; }
;     const float mnC = -mn * C;
; #pragma unroll
;     for (int r = 0; r < 16; ++r) p0[r] = fmaf(p0[r], C, mnC);
; #pragma unroll
;     for (int r = 0; r < 16; ++r) p1[r] = fmaf(p1[r], C, mnC);
; #pragma unroll
;     for (int r = 0; r < 16; ++r) p0[r] = __builtin_amdgcn_exp2f(p0[r]);
; }
; __device__ __forceinline__ void attn_body(const bf16_t* __restrict__ Qb, const bf16_t* __restrict__ Kh, const bf16_t* __restrict__ Vh, const bf16_t* __restrict__ Rh,
;                                           bf16_t* __restrict__ Zb, int seq, char* lds, int wv, bool nowrite) {
;     ...
;     SLOAD(0); SWAIT(); SWRITE(0); __syncthreads();
;     qkt(pA0, pA1, K_lds, R_lds, qr, Qp, r32, hi); partialSM(pA0, pA1, m_reg, mnA, alA);
;     SLOAD(KVBLK);
;     SWAIT(); SWRITE(1); __syncthreads();
	v_mfma_f32_32x32x16_bf16 v[32:47], v[12:15], v[62:65], v[32:47]
	v_mov_b64_e32 v[0:1], s[8:9]
	v_mov_b64_e32 v[2:3], s[10:11]
	v_mov_b64_e32 v[4:5], s[12:13]
	v_mov_b64_e32 v[6:7], s[14:15]
	v_mov_b64_e32 v[8:9], s[16:17]
	v_mov_b64_e32 v[10:11], s[18:19]
	v_mov_b64_e32 v[12:13], s[20:21]
	v_mov_b64_e32 v[14:15], s[22:23]
	s_mov_b64 s[8:9], 0x40000
	v_mfma_f32_32x32x16_bf16 v[16:31], v[58:61], v[62:65], v[16:31]
	s_nop 1
	v_max_f32_e32 v58, v33, v33
	v_max_f32_e32 v59, v32, v32
	v_lshl_add_u64 v[66:67], v[52:53], 0, s[8:9]
	s_mov_b64 s[8:9], 0x60000
	v_max_f32_e32 v58, v59, v58
	v_lshl_add_u64 v[52:53], v[52:53], 0, s[8:9]
	v_max3_f32 v74, v58, v34, v35
	v_lshl_add_u64 v[58:59], s[62:63], 0, v[66:67]
	v_lshl_add_u64 v[62:63], s[62:63], 0, v[52:53]
	v_lshl_add_u64 v[66:67], s[6:7], 0, v[66:67]
	v_lshl_add_u64 v[52:53], s[6:7], 0, v[52:53]
	s_movk_i32 s6, 0x2000
	global_load_dwordx4 v[58:61], v[58:59], off
	s_nop 0
	global_load_dwordx4 v[62:65], v[62:63], off
	s_nop 0
	global_load_dwordx4 v[66:69], v[66:67], off
	s_nop 0
	global_load_dwordx4 v[70:73], v[52:53], off
	v_add_co_u32_e32 v52, vcc, s6, v54
	v_max3_f32 v74, v74, v36, v37
	s_nop 0
	v_addc_co_u32_e32 v53, vcc, 0, v55, vcc
	global_load_dwordx4 v[52:55], v[52:53], off
	v_max3_f32 v74, v74, v38, v39
	v_max3_f32 v74, v74, v40, v41
	v_max3_f32 v74, v74, v42, v43
	v_max3_f32 v74, v74, v44, v45
	v_max3_f32 v74, v74, v46, v47
	v_max3_f32 v74, v74, v16, v17
	v_max3_f32 v74, v74, v18, v19
	v_max3_f32 v74, v74, v20, v21
	v_max3_f32 v74, v74, v22, v23
	v_max3_f32 v74, v74, v24, v25
	v_max3_f32 v74, v74, v26, v27
	v_max3_f32 v74, v74, v28, v29
	v_max3_f32 v74, v74, v30, v31
	v_mov_b32_e32 v78, v74
	s_nop 1
	v_permlane32_swap_b32_e32 v74, v78
	v_max_f32_e32 v78, v78, v78
	v_max_f32_e32 v74, v74, v74
	v_max_f32_e32 v74, v74, v78
	v_add_f32_e32 v78, 0x7149f2ca, v74
	v_max_f32_e32 v74, 0xf149f2ca, v74
	v_cmp_ge_f32_e32 vcc, s88, v78
	v_sub_f32_e32 v78, 0xf149f2ca, v74
	v_mul_f32_e32 v78, 0x3dd53b94, v78
	v_exp_f32_e32 v78, v78
	s_cmp_eq_u64 vcc, exec
	s_cselect_b64 vcc, -1, 0
	v_cndmask_b32_e32 v197, v74, v235, vcc
	s_add_i32 s8, 0, 0x4000
	v_mul_f32_e32 v74, 0xbdd53b94, v197
	v_add_u32_e32 v168, s8, v57
	s_lshl_b64 s[8:9], s[56:57], 18
	v_cndmask_b32_e64 v194, v78, 1.0, vcc
	v_mov_b32_e32 v78, v74
	s_add_u32 s8, s72, s8
	v_fmamk_f32 v32, v32, 0x3dd53b94, v74
	v_fmamk_f32 v33, v33, 0x3dd53b94, v74
	v_fmamk_f32 v34, v34, 0x3dd53b94, v74
	v_fmamk_f32 v35, v35, 0x3dd53b94, v74
	v_fmamk_f32 v36, v36, 0x3dd53b94, v74
	v_fmamk_f32 v37, v37, 0x3dd53b94, v74
	v_fmamk_f32 v38, v38, 0x3dd53b94, v74
	v_fmamk_f32 v39, v39, 0x3dd53b94, v74
	v_fmamk_f32 v40, v40, 0x3dd53b94, v74
	v_fmamk_f32 v41, v41, 0x3dd53b94, v74
	v_fmamk_f32 v42, v42, 0x3dd53b94, v74
	v_fmamk_f32 v43, v43, 0x3dd53b94, v74
	v_fmamk_f32 v44, v44, 0x3dd53b94, v74
	v_fmamk_f32 v45, v45, 0x3dd53b94, v74
	v_fmamk_f32 v46, v46, 0x3dd53b94, v74
	v_fmac_f32_e32 v78, 0x3dd53b94, v47
	v_pk_fma_f32 v[138:139], v[18:19], s[36:37], v[74:75] op_sel_hi:[1,0,0]
	s_addc_u32 s9, s73, s9
	v_and_b32_e32 v18, 7, v56
	v_pk_fma_f32 v[140:141], v[16:17], s[36:37], v[74:75] op_sel_hi:[1,0,0]
	v_exp_f32_e32 v162, v32
	v_exp_f32_e32 v205, v33
	v_exp_f32_e32 v149, v34
	v_exp_f32_e32 v163, v35
	v_exp_f32_e32 v150, v36
	v_exp_f32_e32 v161, v37
	v_exp_f32_e32 v151, v38
	v_exp_f32_e32 v160, v39
	v_exp_f32_e32 v152, v40
	v_exp_f32_e32 v155, v41
	v_exp_f32_e32 v153, v42
	v_exp_f32_e32 v154, v43
	v_exp_f32_e32 v145, v44
	v_exp_f32_e32 v147, v45
	v_exp_f32_e32 v144, v46
	v_exp_f32_e32 v146, v78
	v_lshl_add_u64 v[16:17], s[8:9], 0, v[50:51]
	v_lshlrev_b32_e32 v18, 4, v18
	v_mov_b32_e32 v19, v213
	s_waitcnt vmcnt(0)
	v_lshl_add_u64 v[156:157], v[16:17], 0, v[18:19]
	v_and_b32_e32 v16, 0xf0, v75
	v_pk_fma_f32 v[134:135], v[30:31], s[36:37], v[74:75] op_sel_hi:[1,0,0]
	v_pk_fma_f32 v[136:137], v[28:29], s[36:37], v[74:75] op_sel_hi:[1,0,0]
	v_pk_fma_f32 v[142:143], v[26:27], s[36:37], v[74:75] op_sel_hi:[1,0,0]
	v_pk_fma_f32 v[128:129], v[24:25], s[36:37], v[74:75] op_sel_hi:[1,0,0]
	v_pk_fma_f32 v[130:131], v[22:23], s[36:37], v[74:75] op_sel_hi:[1,0,0]
	v_pk_fma_f32 v[132:133], v[20:21], s[36:37], v[74:75] op_sel_hi:[1,0,0]
	s_waitcnt vmcnt(4)
	ds_write_b128 v170, v[58:61] offset:16384
	s_waitcnt vmcnt(3)
	ds_write_b128 v171, v[62:65] offset:16384
	s_waitcnt vmcnt(2)
	ds_write_b128 v172, v[66:69] offset:49152
	s_waitcnt vmcnt(1)
	ds_write_b128 v173, v[70:73] offset:49152
	s_waitcnt vmcnt(0)
	ds_write_b128 v196, v[52:55]
	v_or3_b32 v158, v158, s3, v16
	v_mov_b64_e32 v[62:63], v[14:15]
	v_mov_b64_e32 v[46:47], v[14:15]
	v_mov_b64_e32 v[30:31], v[14:15]
	v_cmp_gt_u32_e64 s[6:7], 32, v77
	s_mov_b32 s3, -1
	v_mov_b64_e32 v[60:61], v[12:13]
	v_mov_b64_e32 v[58:59], v[10:11]
	v_mov_b64_e32 v[56:57], v[8:9]
	v_mov_b64_e32 v[54:55], v[6:7]
	v_mov_b64_e32 v[52:53], v[4:5]
	v_mov_b64_e32 v[50:51], v[2:3]
	v_mov_b64_e32 v[48:49], v[0:1]
	v_mov_b64_e32 v[44:45], v[12:13]
	v_mov_b64_e32 v[42:43], v[10:11]
	v_mov_b64_e32 v[40:41], v[8:9]
	v_mov_b64_e32 v[38:39], v[6:7]
	v_mov_b64_e32 v[36:37], v[4:5]
	v_mov_b64_e32 v[34:35], v[2:3]
	v_mov_b64_e32 v[32:33], v[0:1]
	v_mov_b64_e32 v[28:29], v[12:13]
	v_mov_b64_e32 v[26:27], v[10:11]
	v_mov_b64_e32 v[24:25], v[8:9]
	v_mov_b64_e32 v[22:23], v[6:7]
	v_mov_b64_e32 v[20:21], v[4:5]
	v_mov_b64_e32 v[18:19], v[2:3]
	v_mov_b64_e32 v[16:17], v[0:1]
	v_add_u32_e32 v242, 0x30080000, v158
	v_add_u32_e32 v243, 0x300a0000, v158
	v_add_u32_e32 v244, 0x28080000, v158
	v_add_u32_e32 v245, 0x280a0000, v158
	v_add_u32_e32 v246, 0x3e004000, v156
	v_add_u32_e32 v247, 0x1c800, v169
	v_add_u32_e32 v248, 0x1c800, v170
	v_add_u32_e32 v249, 0x1c800, v171
	s_waitcnt lgkmcnt(0)
	s_barrier
; __device__ __forceinline__ void finishSM(f32x16& p0, f32x16& p1, float alpha, float& l_reg, bf16x8& pa0, bf16x8& pa1, bf16x8& pa2, bf16x8& pa3) {
; #pragma unroll
;     for (int r = 0; r < 16; ++r) p1[r] = __builtin_amdgcn_exp2f(p1[r]);
;     float ps = 0;
; #pragma unroll
;     for (int r = 0; r < 16; ++r) ps += p0[r];
; #pragma unroll
;     for (int r = 0; r < 16; ++r) ps += p1[r];
;     { auto rr = __builtin_amdgcn_permlane32_swap(__float_as_uint(ps), __float_as_uint(ps), false, false);
;       ps = __uint_as_float(rr[0]) + __uint_as_float(rr[1]); }
;     l_reg = l_reg * alpha + ps;
; __device__ __forceinline__ void qkt(f32x16& p0, f32x16& p1, const char* Ks, const char* Rs, const bf16x8* qr, const char* Qp, int r32, int hi) {
;     p0 = f32x16{}; p1 = f32x16{};
; #pragma unroll
;     for (int d0 = 0; d0 < 8; ++d0) { const int cb = (d0 * 16 + hi * 8) * 2;
;         const bf16x8 b0 = *reinterpret_cast<const bf16x8*>(Ks + KSWZ(r32, cb));
;         const bf16x8 b1 = *reinterpret_cast<const bf16x8*>(Ks + KSWZ(32 + r32, cb));
;         p0 = __builtin_amdgcn_mfma_f32_32x32x16_bf16(b0, qr[d0], p0, 0, 0, 0);
;         p1 = __builtin_amdgcn_mfma_f32_32x32x16_bf16(b1, qr[d0], p1, 0, 0, 0); }
; #pragma unroll
;     for (int d0 = 0; d0 < 4; ++d0) { const int cb = (d0 * 16 + hi * 8) * 2;
;         const bf16x8 b0 = *reinterpret_cast<const bf16x8*>(Rs + RSWZ(r32, cb));
;         const bf16x8 b1 = *reinterpret_cast<const bf16x8*>(Rs + RSWZ(32 + r32, cb));
;         const bf16x8 qq = *reinterpret_cast<const bf16x8*>(Qp + RSWZ(r32, cb));
;         p0 = __builtin_amdgcn_mfma_f32_32x32x16_bf16(b0, qq, p0, 0, 0, 0);
;         p1 = __builtin_amdgcn_mfma_f32_32x32x16_bf16(b1, qq, p1, 0, 0, 0); }
; }
.LBB0_608:
	ds_read_b128 v[64:67], v174 offset:49152
	ds_read_b128 v[68:71], v174 offset:57344
	ds_read_b128 v[198:201], v180 offset:49152
	ds_read_b128 v[206:209], v180 offset:57344
	s_add_i32 s8, 0, 0x12000
	v_add_f32_e32 v148, 0, v162
	s_waitcnt lgkmcnt(3)
	v_mfma_f32_32x32x16_bf16 v[80:95], v[64:67], v[120:123], 0
	v_add_f32_e32 v148, v205, v148
	v_add_f32_e32 v148, v149, v148
	v_add_f32_e32 v148, v163, v148
	v_add_f32_e32 v148, v150, v148
	v_add_f32_e32 v148, v161, v148
	v_add_f32_e32 v148, v151, v148
	v_add_f32_e32 v148, v160, v148
	s_waitcnt lgkmcnt(2)
	v_mfma_f32_32x32x16_bf16 v[64:79], v[68:71], v[120:123], 0
	v_add_f32_e32 v148, v152, v148
	v_add_f32_e32 v148, v155, v148
	v_add_f32_e32 v148, v153, v148
	v_add_f32_e32 v148, v154, v148
	v_exp_f32_e32 v140, v140
	v_add_f32_e32 v148, v145, v148
	v_exp_f32_e32 v141, v141
	s_waitcnt lgkmcnt(1)
	v_mfma_f32_32x32x16_bf16 v[80:95], v[198:201], v[124:127], v[80:95]
	v_add_f32_e32 v148, v147, v148
	v_exp_f32_e32 v138, v138
	v_add_f32_e32 v148, v144, v148
	v_exp_f32_e32 v139, v139
	v_add_f32_e32 v148, v146, v148
	v_exp_f32_e32 v132, v132
	v_add_f32_e32 v148, v140, v148
	s_waitcnt lgkmcnt(0)
	v_mfma_f32_32x32x16_bf16 v[64:79], v[206:209], v[124:127], v[64:79]
	ds_read_b128 v[198:201], v182 offset:49152
	ds_read_b128 v[206:209], v182 offset:57344
	v_exp_f32_e32 v133, v133
	v_add_f32_e32 v148, v141, v148
	v_exp_f32_e32 v130, v130
	v_add_f32_e32 v148, v138, v148
	v_exp_f32_e32 v131, v131
	v_add_f32_e32 v148, v139, v148
	s_waitcnt lgkmcnt(1)
	v_mfma_f32_32x32x16_bf16 v[80:95], v[198:201], v[116:119], v[80:95]
	v_exp_f32_e32 v128, v128
	v_add_f32_e32 v148, v132, v148
	v_exp_f32_e32 v129, v129
	v_add_f32_e32 v148, v133, v148
	v_exp_f32_e32 v142, v142
	v_add_f32_e32 v148, v130, v148
	v_exp_f32_e32 v143, v143
	s_waitcnt lgkmcnt(0)
	v_mfma_f32_32x32x16_bf16 v[64:79], v[206:209], v[116:119], v[64:79]
	ds_read_b128 v[198:201], v184 offset:49152
	ds_read_b128 v[206:209], v184 offset:57344
	v_add_f32_e32 v148, v131, v148
	v_exp_f32_e32 v136, v136
	v_add_f32_e32 v148, v128, v148
	v_exp_f32_e32 v137, v137
	v_add_f32_e32 v148, v129, v148
	v_exp_f32_e32 v134, v134
	s_waitcnt lgkmcnt(1)
	v_mfma_f32_32x32x16_bf16 v[80:95], v[198:201], v[112:115], v[80:95]
	v_add_f32_e32 v148, v142, v148
	v_exp_f32_e32 v135, v135
	v_add_f32_e32 v148, v143, v148
	v_add_f32_e32 v148, v136, v148
	v_add_f32_e32 v148, v137, v148
	v_add_f32_e32 v148, v134, v148
	s_waitcnt lgkmcnt(0)
	v_mfma_f32_32x32x16_bf16 v[64:79], v[206:209], v[112:115], v[64:79]
	ds_read_b128 v[198:201], v185 offset:49152
	ds_read_b128 v[206:209], v185 offset:57344
	s_waitcnt lgkmcnt(1)
	v_mfma_f32_32x32x16_bf16 v[80:95], v[198:201], v[108:111], v[80:95]
	s_waitcnt lgkmcnt(0)
	v_mfma_f32_32x32x16_bf16 v[64:79], v[206:209], v[108:111], v[64:79]
	ds_read_b128 v[198:201], v183 offset:49152
	ds_read_b128 v[206:209], v183 offset:57344
	s_waitcnt lgkmcnt(1)
	v_mfma_f32_32x32x16_bf16 v[80:95], v[198:201], v[104:107], v[80:95]
	s_waitcnt lgkmcnt(0)
	v_mfma_f32_32x32x16_bf16 v[64:79], v[206:209], v[104:107], v[64:79]
	ds_read_b128 v[198:201], v181 offset:49152
	ds_read_b128 v[206:209], v181 offset:57344
	s_waitcnt lgkmcnt(1)
	v_mfma_f32_32x32x16_bf16 v[80:95], v[198:201], v[100:103], v[80:95]
	s_waitcnt lgkmcnt(0)
	v_mfma_f32_32x32x16_bf16 v[64:79], v[206:209], v[100:103], v[64:79]
	ds_read_b128 v[198:201], v179 offset:49152
	ds_read_b128 v[206:209], v179 offset:57344
	s_waitcnt lgkmcnt(1)
	v_mfma_f32_32x32x16_bf16 v[80:95], v[198:201], v[96:99], v[80:95]
	v_add_u32_e32 v199, s8, v186
	v_add_u32_e32 v198, s8, v188
	s_waitcnt lgkmcnt(0)
	v_mfma_f32_32x32x16_bf16 v[64:79], v[206:209], v[96:99], v[64:79]
	ds_read_b128 v[200:203], v199
	ds_read_b128 v[206:209], v199 offset:4096
	ds_read_b128 v[214:217], v177
	s_waitcnt lgkmcnt(0)
	v_mfma_f32_32x32x16_bf16 v[80:95], v[200:203], v[214:217], v[80:95]
	v_mfma_f32_32x32x16_bf16 v[64:79], v[206:209], v[214:217], v[64:79]
	ds_read_b128 v[200:203], v198
	ds_read_b128 v[206:209], v198 offset:4096
	ds_read_b128 v[214:217], v175
	s_waitcnt lgkmcnt(0)
	v_mfma_f32_32x32x16_bf16 v[80:95], v[200:203], v[214:217], v[80:95]
	v_add_u32_e32 v200, s8, v190
	v_add_u32_e32 v201, s8, v192
	v_add_f32_e32 v202, v135, v148
	v_mov_b32_e32 v203, v202
	s_nop 1
	v_permlane32_swap_b32_e32 v202, v203
	v_mfma_f32_32x32x16_bf16 v[64:79], v[206:209], v[214:217], v[64:79]
	ds_read_b128 v[206:209], v200
	ds_read_b128 v[214:217], v200 offset:4096
	ds_read_b128 v[218:221], v178
	s_waitcnt lgkmcnt(0)
	v_mfma_f32_32x32x16_bf16 v[80:95], v[206:209], v[218:221], v[80:95]
	v_mfma_f32_32x32x16_bf16 v[64:79], v[214:217], v[218:221], v[64:79]
	ds_read_b128 v[206:209], v201
	ds_read_b128 v[214:217], v201 offset:4096
	ds_read_b128 v[218:221], v176
	v_cvt_pk_bf16_f32 v148, v162, v205
	v_cvt_pk_bf16_f32 v149, v149, v163
	v_cvt_pk_bf16_f32 v150, v150, v161
	v_cvt_pk_bf16_f32 v151, v151, v160
	v_cvt_pk_bf16_f32 v152, v152, v155
	v_cvt_pk_bf16_f32 v153, v153, v154
	s_waitcnt lgkmcnt(0)
; #define SBAR() __builtin_amdgcn_sched_barrier(0)
; #define SWRITE(b) do { *(bf16x8*)(V_lds + (b) * SHM_V + vst0) = vs0; *(bf16x8*)(V_lds + (b) * SHM_V + vst1) = vs1; const int kc = sc * 2; \
;     *(bf16x8*)(K_lds + (b) * SHM_K + KSWZ(sr, kc)) = ks0; *(bf16x8*)(K_lds + (b) * SHM_K + KSWZ(32 + sr, kc)) = ks1; \
;     *(bf16x8*)(R_lds + (b) * SHM_R + RSWZ(rr, rc * 2)) = rs0; } while (0)
; #define SWAIT() asm volatile("s_waitcnt vmcnt(0)" ::: "memory")
; template <int D0> __device__ __forceinline__ void pv_one(f32x16& od, int vb, bf16x8 pa0, bf16x8 pa1, bf16x8 pa2, bf16x8 pa3) {
;     const s16x4 l0 = tr_read<v_rd_off(D0, 0, 0)>(vb), h0 = tr_read<v_rd_off(D0, 0, 1)>(vb), l1 = tr_read<v_rd_off(D0, 1, 0)>(vb), h1 = tr_read<v_rd_off(D0, 1, 1)>(vb);
;     const s16x4 l2 = tr_read<v_rd_off(D0, 2, 0)>(vb), h2 = tr_read<v_rd_off(D0, 2, 1)>(vb), l3 = tr_read<v_rd_off(D0, 3, 0)>(vb), h3 = tr_read<v_rd_off(D0, 3, 1)>(vb);
;     asm volatile("s_waitcnt lgkmcnt(0)" ::: "memory"); SBAR();
;     ...
;     od = __builtin_amdgcn_mfma_f32_32x32x16_bf16(pa0, PK(l0, h0), od, 0, 0, 0);
;     od = __builtin_amdgcn_mfma_f32_32x32x16_bf16(pa1, PK(l1, h1), od, 0, 0, 0);
;     od = __builtin_amdgcn_mfma_f32_32x32x16_bf16(pa2, PK(l2, h2), od, 0, 0, 0);
;     od = __builtin_amdgcn_mfma_f32_32x32x16_bf16(pa3, PK(l3, h3), od, 0, 0, 0);
;     ...
; }
; __device__ __forceinline__ void pv_d0(f32x16* o, int vb, bf16x8 pa0, bf16x8 pa1, bf16x8 pa2, bf16x8 pa3) {
;     pv_one<0>(o[0], vb, pa0, pa1, pa2, pa3); pv_one<1>(o[1], vb, pa0, pa1, pa2, pa3); pv_one<2>(o[2], vb, pa0, pa1, pa2, pa3); pv_one<3>(o[3], vb, pa0, pa1, pa2, pa3);
; __device__ __forceinline__ void attn_body(const bf16_t* __restrict__ Qb, const bf16_t* __restrict__ Kh, const bf16_t* __restrict__ Vh, const bf16_t* __restrict__ Rh,
;                                           bf16_t* __restrict__ Zb, int seq, char* lds, int wv, bool nowrite) {
;     ...
;     for (int j = 1; j + 1 < NT; j += 2) {
;         SBAR(); qkt(pB0, pB1, K_lds + SHM_K, R_lds + SHM_R, qr, Qp, r32, hi);
;         finishSM(pA0, pA1, alA, l_reg, pa0, pa1, pa2, pa3); SBAR();
;         SLOAD((j + 1) * KVBLK); SBAR();
;         pv_d0(o, vb0, pa0, pa1, pa2, pa3); partialSM(pB0, pB1, m_reg, mnB, alB);
;         __syncthreads(); SWAIT(); SWRITE(0);
	v_mfma_f32_32x32x16_bf16 v[80:95], v[206:209], v[218:221], v[80:95]
	v_cvt_pk_bf16_f32 v154, v145, v147
	v_cvt_pk_bf16_f32 v155, v144, v146
	v_cvt_pk_bf16_f32 v204, v140, v141
	v_cvt_pk_bf16_f32 v205, v138, v139
	v_cvt_pk_bf16_f32 v206, v132, v133
	v_permlane32_swap_b32_e32 v148, v150
	v_mfma_f32_32x32x16_bf16 v[64:79], v[214:217], v[218:221], v[64:79]
	v_cvt_pk_bf16_f32 v207, v130, v131
	v_permlane32_swap_b32_e32 v204, v206
	v_cvt_pk_bf16_f32 v208, v128, v129
	v_cvt_pk_bf16_f32 v209, v142, v143
	v_cvt_pk_bf16_f32 v210, v136, v137
	v_cvt_pk_bf16_f32 v211, v134, v135
	v_permlane32_swap_b32_e32 v149, v151
	v_permlane32_swap_b32_e32 v152, v154
	v_permlane32_swap_b32_e32 v153, v155
	v_permlane32_swap_b32_e32 v205, v207
	v_permlane32_swap_b32_e32 v208, v210
	v_permlane32_swap_b32_e32 v209, v211
	global_load_dwordx4 v[128:131], v242, s[44:45]
	global_load_dwordx4 v[132:135], v243, s[44:45]
	global_load_dwordx4 v[136:139], v244, s[44:45]
	global_load_dwordx4 v[140:143], v245, s[44:45]
	global_load_dwordx4 v[144:147], v246, s[44:45]
	v_add_u32_e32 v242, 0x40000, v242
	v_add_u32_e32 v243, 0x40000, v243
	v_add_u32_e32 v244, 0x40000, v244
	v_add_u32_e32 v245, 0x40000, v245
	v_add_u32_e32 v246, 0x2000, v246
	ds_read_b64_tr_b16 v[214:215], v169 offset:0
	ds_read_b64_tr_b16 v[216:217], v169 offset:0x800
	ds_read_b64_tr_b16 v[218:219], v169 offset:0x1000
	ds_read_b64_tr_b16 v[220:221], v169 offset:0x1800
	ds_read_b64_tr_b16 v[224:225], v169 offset:0x2000
	ds_read_b64_tr_b16 v[226:227], v169 offset:0x2800
	ds_read_b64_tr_b16 v[238:239], v169 offset:0x3000
	ds_read_b64_tr_b16 v[240:241], v169 offset:0x3800
	s_waitcnt lgkmcnt(0)
	s_nop 0
	v_mfma_f32_32x32x16_bf16 v[0:15], v[148:151], v[214:217], v[0:15]
	ds_read_b64_tr_b16 v[214:215], v169 offset:0x200
	ds_read_b64_tr_b16 v[216:217], v169 offset:0xa00
	v_mfma_f32_32x32x16_bf16 v[0:15], v[152:155], v[218:221], v[0:15]
	ds_read_b64_tr_b16 v[218:219], v169 offset:0x1200
	ds_read_b64_tr_b16 v[220:221], v169 offset:0x1a00
	v_mfma_f32_32x32x16_bf16 v[0:15], v[204:207], v[224:227], v[0:15]
	ds_read_b64_tr_b16 v[224:225], v169 offset:0x2200
	ds_read_b64_tr_b16 v[226:227], v169 offset:0x2a00
	v_mfma_f32_32x32x16_bf16 v[0:15], v[208:211], v[238:241], v[0:15]
	ds_read_b64_tr_b16 v[238:239], v169 offset:0x3200
	ds_read_b64_tr_b16 v[240:241], v169 offset:0x3a00
	s_waitcnt lgkmcnt(0)
	v_mfma_f32_32x32x16_bf16 v[48:63], v[148:151], v[214:217], v[48:63]
	ds_read_b64_tr_b16 v[214:215], v169 offset:0x400
	ds_read_b64_tr_b16 v[216:217], v169 offset:0xc00
	v_mfma_f32_32x32x16_bf16 v[48:63], v[152:155], v[218:221], v[48:63]
	ds_read_b64_tr_b16 v[218:219], v169 offset:0x1400
	ds_read_b64_tr_b16 v[220:221], v169 offset:0x1c00
	v_mfma_f32_32x32x16_bf16 v[48:63], v[204:207], v[224:227], v[48:63]
	ds_read_b64_tr_b16 v[224:225], v169 offset:0x2400
	ds_read_b64_tr_b16 v[226:227], v169 offset:0x2c00
	v_mfma_f32_32x32x16_bf16 v[48:63], v[208:211], v[238:241], v[48:63]
	ds_read_b64_tr_b16 v[238:239], v169 offset:0x3400
	ds_read_b64_tr_b16 v[240:241], v169 offset:0x3c00
	s_waitcnt lgkmcnt(0)
	v_mfma_f32_32x32x16_bf16 v[32:47], v[148:151], v[214:217], v[32:47]
	ds_read_b64_tr_b16 v[214:215], v169 offset:0x600
	ds_read_b64_tr_b16 v[216:217], v169 offset:0xe00
	v_mfma_f32_32x32x16_bf16 v[32:47], v[152:155], v[218:221], v[32:47]
	ds_read_b64_tr_b16 v[218:219], v169 offset:0x1600
	ds_read_b64_tr_b16 v[220:221], v169 offset:0x1e00
	v_mfma_f32_32x32x16_bf16 v[32:47], v[204:207], v[224:227], v[32:47]
	ds_read_b64_tr_b16 v[224:225], v169 offset:0x2600
	ds_read_b64_tr_b16 v[226:227], v169 offset:0x2e00
	v_mfma_f32_32x32x16_bf16 v[32:47], v[208:211], v[238:241], v[32:47]
	ds_read_b64_tr_b16 v[238:239], v169 offset:0x3600
	ds_read_b64_tr_b16 v[240:241], v169 offset:0x3e00
	s_waitcnt lgkmcnt(0)
	v_mfma_f32_32x32x16_bf16 v[16:31], v[148:151], v[214:217], v[16:31]
	v_max_f32_e32 v148, v81, v81
	v_max_f32_e32 v149, v80, v80
	v_max_f32_e32 v148, v149, v148
	v_max3_f32 v148, v148, v82, v83
	v_max3_f32 v148, v148, v84, v85
	v_max3_f32 v148, v148, v86, v87
	v_max3_f32 v148, v148, v88, v89
	v_max3_f32 v148, v148, v90, v91
	v_max3_f32 v148, v148, v92, v93
	v_mfma_f32_32x32x16_bf16 v[16:31], v[152:155], v[218:221], v[16:31]
	v_max3_f32 v148, v148, v94, v95
	v_max3_f32 v148, v148, v64, v65
	v_max3_f32 v148, v148, v66, v67
	v_max3_f32 v148, v148, v68, v69
	v_max3_f32 v148, v148, v70, v71
	v_max3_f32 v148, v148, v72, v73
	v_max3_f32 v148, v148, v74, v75
	v_max3_f32 v148, v148, v76, v77
	v_mfma_f32_32x32x16_bf16 v[16:31], v[204:207], v[224:227], v[16:31]
	v_max3_f32 v148, v148, v78, v79
	v_mov_b32_e32 v149, v148
	s_nop 1
	v_permlane32_swap_b32_e32 v148, v149
	v_max_f32_e32 v149, v149, v149
	v_max_f32_e32 v148, v148, v148
	v_max_f32_e32 v148, v148, v149
	v_sub_f32_e32 v149, v148, v197
	v_cmp_ge_f32_e32 vcc, s88, v149
	v_max_f32_e32 v149, v197, v197
	v_max_f32_e32 v148, v149, v148
	v_mfma_f32_32x32x16_bf16 v[16:31], v[208:211], v[238:241], v[16:31]
	v_sub_f32_e32 v149, v197, v148
	v_mul_f32_e32 v149, 0x3dd53b94, v149
	v_exp_f32_e32 v149, v149
	s_cmp_eq_u64 vcc, exec
	s_cselect_b64 s[8:9], -1, 0
	s_waitcnt vmcnt(0)
	v_cndmask_b32_e64 v204, v149, 1.0, s[8:9]
	ds_write_b128 v248, v[128:131]
	ds_write_b128 v249, v[132:135]
	ds_write_b128 v172, v[136:139] offset:32768
	ds_write_b128 v173, v[140:143] offset:32768
	v_add_u32_e32 v128, 0x10000, v195
	v_cmp_gt_f32_e32 vcc, 1.0, v204
	ds_write_b128 v128, v[144:147]
	s_cbranch_vccz .LBB0_612
; __device__ __forceinline__ void partialSM(f32x16& p0, f32x16& p1, float& m_reg, float& mn, float& alpha) {
;     ...
;     if (__builtin_expect(__all(pmax - m_reg <= THR / SCALE), 1)) { mn = m_reg; alpha = 1.f; }
;     else { mn = fmaxf(m_reg, pmax); alpha = __builtin_amdgcn_exp2f((m_reg - mn) * C); m_reg = mn; }
;     const float mnC = -mn * C;
; #pragma unroll
;     for (int r = 0; r < 16; ++r) p0[r] = fmaf(p0[r], C, mnC);
; #pragma unroll
;     for (int r = 0; r < 16; ++r) p1[r] = fmaf(p1[r], C, mnC);
; #pragma unroll
;     for (int r = 0; r < 16; ++r) p0[r] = __builtin_amdgcn_exp2f(p0[r]);
	s_and_saveexec_b64 s[10:11], s[6:7]
	ds_write_b32 v166, v204 offset:128
	s_or_b64 exec, exec, s[10:11]
	s_waitcnt lgkmcnt(0)
	v_add_u32_e32 v140, s1, v212
	ds_read_b128 v[128:131], v140 offset:224
	ds_read_b128 v[132:135], v140 offset:192
	ds_read_b128 v[136:139], v140 offset:160
	ds_read_b128 v[140:143], v140 offset:128
	s_waitcnt lgkmcnt(3)
	v_pk_mul_f32 v[12:13], v[12:13], v[128:129]
	s_waitcnt lgkmcnt(2)
	v_pk_mul_f32 v[8:9], v[8:9], v[132:133]
	s_waitcnt lgkmcnt(1)
	v_pk_mul_f32 v[4:5], v[4:5], v[136:137]
	v_pk_mul_f32 v[14:15], v[14:15], v[130:131]
	v_pk_mul_f32 v[10:11], v[10:11], v[134:135]
	v_pk_mul_f32 v[6:7], v[6:7], v[138:139]
	s_waitcnt lgkmcnt(0)
	v_pk_mul_f32 v[2:3], v[2:3], v[142:143]
	v_pk_mul_f32 v[0:1], v[0:1], v[140:141]
	v_pk_mul_f32 v[60:61], v[60:61], v[128:129]
	v_pk_mul_f32 v[56:57], v[56:57], v[132:133]
	v_pk_mul_f32 v[52:53], v[52:53], v[136:137]
	v_pk_mul_f32 v[62:63], v[62:63], v[130:131]
	v_pk_mul_f32 v[58:59], v[58:59], v[134:135]
	v_pk_mul_f32 v[54:55], v[54:55], v[138:139]
	v_pk_mul_f32 v[50:51], v[50:51], v[142:143]
	v_pk_mul_f32 v[48:49], v[48:49], v[140:141]
	v_pk_mul_f32 v[44:45], v[44:45], v[128:129]
	v_pk_mul_f32 v[40:41], v[40:41], v[132:133]
	v_pk_mul_f32 v[36:37], v[36:37], v[136:137]
	v_pk_mul_f32 v[46:47], v[46:47], v[130:131]
	v_pk_mul_f32 v[42:43], v[42:43], v[134:135]
	v_pk_mul_f32 v[38:39], v[38:39], v[138:139]
	v_pk_mul_f32 v[34:35], v[34:35], v[142:143]
	v_pk_mul_f32 v[32:33], v[32:33], v[140:141]
	v_pk_mul_f32 v[28:29], v[28:29], v[128:129]
	v_pk_mul_f32 v[24:25], v[24:25], v[132:133]
	v_pk_mul_f32 v[20:21], v[20:21], v[136:137]
	v_pk_mul_f32 v[30:31], v[30:31], v[130:131]
	v_pk_mul_f32 v[26:27], v[26:27], v[134:135]
	v_pk_mul_f32 v[22:23], v[22:23], v[138:139]
	v_pk_mul_f32 v[18:19], v[18:19], v[142:143]
	v_pk_mul_f32 v[16:17], v[16:17], v[140:141]
.LBB0_612:
	v_cndmask_b32_e64 v197, v148, v197, s[8:9]
	v_mul_f32_e32 v144, 0xbdd53b94, v197
	v_fmamk_f32 v80, v80, 0x3dd53b94, v144
	v_fmamk_f32 v81, v81, 0x3dd53b94, v144
	v_fmamk_f32 v82, v82, 0x3dd53b94, v144
	v_fmamk_f32 v83, v83, 0x3dd53b94, v144
	v_fmamk_f32 v84, v84, 0x3dd53b94, v144
	v_fmamk_f32 v85, v85, 0x3dd53b94, v144
	v_fmamk_f32 v86, v86, 0x3dd53b94, v144
	v_fmamk_f32 v87, v87, 0x3dd53b94, v144
	v_fmamk_f32 v88, v88, 0x3dd53b94, v144
	v_fmamk_f32 v89, v89, 0x3dd53b94, v144
	v_fmamk_f32 v90, v90, 0x3dd53b94, v144
	v_fmamk_f32 v91, v91, 0x3dd53b94, v144
	v_fmamk_f32 v92, v92, 0x3dd53b94, v144
	v_fmamk_f32 v93, v93, 0x3dd53b94, v144
	v_fmamk_f32 v94, v94, 0x3dd53b94, v144
	v_fmamk_f32 v95, v95, 0x3dd53b94, v144
	v_fmamk_f32 v206, v68, 0x3dd53b94, v144
	v_fmamk_f32 v148, v71, 0x3dd53b94, v144
	v_fmamk_f32 v149, v72, 0x3dd53b94, v144
	v_fmamk_f32 v207, v77, 0x3dd53b94, v144
	v_fmamk_f32 v153, v64, 0x3dd53b94, v144
	v_fmamk_f32 v154, v65, 0x3dd53b94, v144
	v_fmamk_f32 v155, v66, 0x3dd53b94, v144
	v_fmamk_f32 v205, v67, 0x3dd53b94, v144
	v_fmamk_f32 v146, v69, 0x3dd53b94, v144
	v_fmamk_f32 v147, v70, 0x3dd53b94, v144
	v_fmamk_f32 v150, v73, 0x3dd53b94, v144
	v_fmamk_f32 v151, v74, 0x3dd53b94, v144
	v_fmamk_f32 v152, v75, 0x3dd53b94, v144
	v_fmamk_f32 v145, v76, 0x3dd53b94, v144
	v_exp_f32_e32 v141, v80
	v_exp_f32_e32 v143, v81
	v_exp_f32_e32 v139, v82
	v_exp_f32_e32 v142, v83
	v_exp_f32_e32 v138, v84
	v_exp_f32_e32 v140, v85
	v_exp_f32_e32 v136, v86
	v_exp_f32_e32 v137, v87
	v_exp_f32_e32 v133, v88
	v_exp_f32_e32 v135, v89
	v_exp_f32_e32 v132, v90
	v_exp_f32_e32 v134, v91
	v_exp_f32_e32 v129, v92
	v_exp_f32_e32 v131, v93
	v_exp_f32_e32 v128, v94
	v_exp_f32_e32 v130, v95
	v_fmamk_f32 v208, v78, 0x3dd53b94, v144
	v_fmac_f32_e32 v144, 0x3dd53b94, v79
	s_waitcnt lgkmcnt(0)
	s_barrier
	ds_read_b128 v[64:67], v174 offset:32768
	ds_read_b128 v[68:71], v174 offset:40960
	ds_read_b128 v[214:217], v180 offset:32768
	ds_read_b128 v[218:221], v180 offset:40960
	v_exp_f32_e32 v209, v153
	v_exp_f32_e32 v210, v154
	s_waitcnt lgkmcnt(3)
	v_mfma_f32_32x32x16_bf16 v[80:95], v[64:67], v[120:123], 0
	v_exp_f32_e32 v211, v155
	v_exp_f32_e32 v205, v205
	v_exp_f32_e32 v146, v146
	v_exp_f32_e32 v147, v147
	v_exp_f32_e32 v145, v145
	v_exp_f32_e32 v144, v144
	s_waitcnt lgkmcnt(2)
	v_mfma_f32_32x32x16_bf16 v[64:79], v[68:71], v[120:123], 0
	s_waitcnt lgkmcnt(1)
	v_mfma_f32_32x32x16_bf16 v[80:95], v[214:217], v[124:127], v[80:95]
	s_waitcnt lgkmcnt(0)
	v_mfma_f32_32x32x16_bf16 v[64:79], v[218:221], v[124:127], v[64:79]
	ds_read_b128 v[214:217], v182 offset:32768
	ds_read_b128 v[218:221], v182 offset:40960
	s_waitcnt lgkmcnt(1)
	v_mfma_f32_32x32x16_bf16 v[80:95], v[214:217], v[116:119], v[80:95]
	s_waitcnt lgkmcnt(0)
	v_mfma_f32_32x32x16_bf16 v[64:79], v[218:221], v[116:119], v[64:79]
	ds_read_b128 v[214:217], v184 offset:32768
	ds_read_b128 v[218:221], v184 offset:40960
	s_waitcnt lgkmcnt(1)
	v_mfma_f32_32x32x16_bf16 v[80:95], v[214:217], v[112:115], v[80:95]
	s_waitcnt lgkmcnt(0)
	v_mfma_f32_32x32x16_bf16 v[64:79], v[218:221], v[112:115], v[64:79]
	ds_read_b128 v[214:217], v185 offset:32768
	ds_read_b128 v[218:221], v185 offset:40960
	s_waitcnt lgkmcnt(1)
	v_mfma_f32_32x32x16_bf16 v[80:95], v[214:217], v[108:111], v[80:95]
	s_waitcnt lgkmcnt(0)
	v_mfma_f32_32x32x16_bf16 v[64:79], v[218:221], v[108:111], v[64:79]
	ds_read_b128 v[214:217], v183 offset:32768
	ds_read_b128 v[218:221], v183 offset:40960
	s_waitcnt lgkmcnt(1)
	v_mfma_f32_32x32x16_bf16 v[80:95], v[214:217], v[104:107], v[80:95]
	s_waitcnt lgkmcnt(0)
	v_mfma_f32_32x32x16_bf16 v[64:79], v[218:221], v[104:107], v[64:79]
	ds_read_b128 v[214:217], v181 offset:32768
	ds_read_b128 v[218:221], v181 offset:40960
	s_waitcnt lgkmcnt(1)
	v_mfma_f32_32x32x16_bf16 v[80:95], v[214:217], v[100:103], v[80:95]
	s_waitcnt lgkmcnt(0)
; #define SBAR() __builtin_amdgcn_sched_barrier(0)
; __device__ __forceinline__ void finishSM(f32x16& p0, f32x16& p1, float alpha, float& l_reg, bf16x8& pa0, bf16x8& pa1, bf16x8& pa2, bf16x8& pa3) {
; #pragma unroll
;     for (int r = 0; r < 16; ++r) p1[r] = __builtin_amdgcn_exp2f(p1[r]);
;     float ps = 0;
; #pragma unroll
;     for (int r = 0; r < 16; ++r) ps += p0[r];
; #pragma unroll
;     for (int r = 0; r < 16; ++r) ps += p1[r];
;     { auto rr = __builtin_amdgcn_permlane32_swap(__float_as_uint(ps), __float_as_uint(ps), false, false);
;       ps = __uint_as_float(rr[0]) + __uint_as_float(rr[1]); }
;     l_reg = l_reg * alpha + ps;
;     ...
;     PK4(p0, 0, pa0); PK4(p0, 8, pa1); PK4(p1, 0, pa2); PK4(p1, 8, pa3);
; __device__ __forceinline__ void attn_body(const bf16_t* __restrict__ Qb, const bf16_t* __restrict__ Kh, const bf16_t* __restrict__ Vh, const bf16_t* __restrict__ Rh,
;                                           bf16_t* __restrict__ Zb, int seq, char* lds, int wv, bool nowrite) {
;     ...
;         SBAR(); qkt(pA0, pA1, K_lds, R_lds, qr, Qp, r32, hi);
;         finishSM(pB0, pB1, alB, l_reg, pa0, pa1, pa2, pa3); SBAR();
;         SLOAD((j + 2) * KVBLK); SBAR();
;         pv_d0(o, vb0 + SHM_V, pa0, pa1, pa2, pa3); partialSM(pA0, pA1, m_reg, mnA, alA);
	v_mfma_f32_32x32x16_bf16 v[64:79], v[218:221], v[100:103], v[64:79]
	ds_read_b128 v[214:217], v179 offset:32768
	ds_read_b128 v[218:221], v179 offset:40960
	s_waitcnt lgkmcnt(1)
	v_mfma_f32_32x32x16_bf16 v[80:95], v[214:217], v[96:99], v[80:95]
	s_waitcnt lgkmcnt(0)
	v_mfma_f32_32x32x16_bf16 v[64:79], v[218:221], v[96:99], v[64:79]
	ds_read_b128 v[214:217], v187
	ds_read_b128 v[218:221], v187 offset:4096
	ds_read_b128 v[224:227], v177
	s_waitcnt lgkmcnt(0)
	v_mfma_f32_32x32x16_bf16 v[80:95], v[214:217], v[224:227], v[80:95]
	v_mfma_f32_32x32x16_bf16 v[64:79], v[218:221], v[224:227], v[64:79]
	ds_read_b128 v[214:217], v189
	ds_read_b128 v[218:221], v189 offset:4096
	ds_read_b128 v[224:227], v175
	s_waitcnt lgkmcnt(0)
	v_mfma_f32_32x32x16_bf16 v[80:95], v[214:217], v[224:227], v[80:95]
	v_mfma_f32_32x32x16_bf16 v[64:79], v[218:221], v[224:227], v[64:79]
	ds_read_b128 v[214:217], v191
	ds_read_b128 v[218:221], v191 offset:4096
	ds_read_b128 v[224:227], v178
	s_waitcnt lgkmcnt(0)
	v_mfma_f32_32x32x16_bf16 v[80:95], v[214:217], v[224:227], v[80:95]
	v_mfma_f32_32x32x16_bf16 v[64:79], v[218:221], v[224:227], v[64:79]
	ds_read_b128 v[214:217], v193
	ds_read_b128 v[218:221], v193 offset:4096
	ds_read_b128 v[224:227], v176
	s_waitcnt lgkmcnt(0)
	v_mfma_f32_32x32x16_bf16 v[80:95], v[214:217], v[224:227], v[80:95]
	v_exp_f32_e32 v215, v148
	v_add_f32_e32 v148, 0, v141
	v_add_f32_e32 v148, v143, v148
	v_add_f32_e32 v148, v139, v148
	v_add_f32_e32 v148, v142, v148
	v_add_f32_e32 v148, v138, v148
	v_add_f32_e32 v148, v140, v148
	v_add_f32_e32 v148, v136, v148
	v_add_f32_e32 v148, v137, v148
	v_add_f32_e32 v148, v133, v148
	v_add_f32_e32 v148, v135, v148
	v_add_f32_e32 v148, v132, v148
	v_add_f32_e32 v148, v134, v148
	v_add_f32_e32 v148, v129, v148
	v_add_f32_e32 v148, v131, v148
	v_add_f32_e32 v148, v128, v148
	v_add_f32_e32 v148, v130, v148
	v_exp_f32_e32 v214, v206
	v_add_f32_e32 v148, v209, v148
	v_add_f32_e32 v148, v210, v148
	v_add_f32_e32 v148, v211, v148
	v_add_f32_e32 v148, v205, v148
	v_exp_f32_e32 v216, v149
	v_add_f32_e32 v148, v214, v148
	v_exp_f32_e32 v217, v150
	v_add_f32_e32 v148, v146, v148
	v_mfma_f32_32x32x16_bf16 v[64:79], v[218:221], v[224:227], v[64:79]
	v_exp_f32_e32 v218, v151
	v_add_f32_e32 v148, v147, v148
	v_exp_f32_e32 v219, v152
	v_add_f32_e32 v148, v215, v148
	v_add_f32_e32 v148, v216, v148
	v_exp_f32_e32 v220, v207
	v_add_f32_e32 v148, v217, v148
	v_exp_f32_e32 v221, v208
	v_add_f32_e32 v148, v218, v148
	v_add_f32_e32 v148, v219, v148
	v_add_f32_e32 v148, v145, v148
	v_add_f32_e32 v148, v220, v148
	v_add_f32_e32 v148, v221, v148
	v_add_f32_e32 v206, v144, v148
	v_mov_b32_e32 v207, v206
	v_cvt_pk_bf16_f32 v148, v141, v143
	v_cvt_pk_bf16_f32 v149, v139, v142
	v_cvt_pk_bf16_f32 v150, v138, v140
	v_cvt_pk_bf16_f32 v151, v136, v137
	s_nop 1
	v_permlane32_swap_b32_e32 v206, v207
	v_permlane32_swap_b32_e32 v148, v150
	v_permlane32_swap_b32_e32 v149, v151
	v_cvt_pk_bf16_f32 v152, v133, v135
	v_cvt_pk_bf16_f32 v153, v132, v134
	v_cvt_pk_bf16_f32 v154, v129, v131
	v_cvt_pk_bf16_f32 v155, v128, v130
	v_cvt_pk_bf16_f32 v208, v209, v210
	v_cvt_pk_bf16_f32 v209, v211, v205
	v_cvt_pk_bf16_f32 v210, v214, v146
	v_cvt_pk_bf16_f32 v211, v147, v215
	v_cvt_pk_bf16_f32 v214, v216, v217
	v_cvt_pk_bf16_f32 v215, v218, v219
	v_cvt_pk_bf16_f32 v216, v145, v220
	v_cvt_pk_bf16_f32 v217, v221, v144
	s_nop 0
	v_permlane32_swap_b32_e32 v152, v154
	v_permlane32_swap_b32_e32 v153, v155
	v_permlane32_swap_b32_e32 v208, v210
	v_permlane32_swap_b32_e32 v209, v211
	v_permlane32_swap_b32_e32 v214, v216
	v_permlane32_swap_b32_e32 v215, v217
	global_load_dwordx4 v[128:131], v242, s[44:45]
	global_load_dwordx4 v[132:135], v243, s[44:45]
	global_load_dwordx4 v[136:139], v244, s[44:45]
	global_load_dwordx4 v[140:143], v245, s[44:45]
	global_load_dwordx4 v[144:147], v246, s[44:45]
	v_add_u32_e32 v242, 0x40000, v242
	v_add_u32_e32 v243, 0x40000, v243
	v_add_u32_e32 v244, 0x40000, v244
	v_add_u32_e32 v245, 0x40000, v245
	v_add_u32_e32 v246, 0x2000, v246
	ds_read_b64_tr_b16 v[160:161], v168 offset:0
	ds_read_b64_tr_b16 v[162:163], v168 offset:0x800
	ds_read_b64_tr_b16 v[218:219], v168 offset:0x1000
	ds_read_b64_tr_b16 v[220:221], v168 offset:0x1800
	ds_read_b64_tr_b16 v[224:225], v168 offset:0x2000
	ds_read_b64_tr_b16 v[226:227], v168 offset:0x2800
	ds_read_b64_tr_b16 v[238:239], v168 offset:0x3000
	ds_read_b64_tr_b16 v[240:241], v168 offset:0x3800
	s_waitcnt lgkmcnt(0)
	s_nop 0
	v_mfma_f32_32x32x16_bf16 v[0:15], v[148:151], v[160:163], v[0:15]
	ds_read_b64_tr_b16 v[160:161], v168 offset:0x200
	ds_read_b64_tr_b16 v[162:163], v168 offset:0xa00
	v_mfma_f32_32x32x16_bf16 v[0:15], v[152:155], v[218:221], v[0:15]
	ds_read_b64_tr_b16 v[218:219], v168 offset:0x1200
	ds_read_b64_tr_b16 v[220:221], v168 offset:0x1a00
	v_mfma_f32_32x32x16_bf16 v[0:15], v[208:211], v[224:227], v[0:15]
	ds_read_b64_tr_b16 v[224:225], v168 offset:0x2200
	ds_read_b64_tr_b16 v[226:227], v168 offset:0x2a00
	v_mfma_f32_32x32x16_bf16 v[0:15], v[214:217], v[238:241], v[0:15]
	ds_read_b64_tr_b16 v[238:239], v168 offset:0x3200
	ds_read_b64_tr_b16 v[240:241], v168 offset:0x3a00
	s_waitcnt lgkmcnt(0)
	v_mfma_f32_32x32x16_bf16 v[48:63], v[148:151], v[160:163], v[48:63]
	ds_read_b64_tr_b16 v[160:161], v168 offset:0x400
	ds_read_b64_tr_b16 v[162:163], v168 offset:0xc00
	v_mfma_f32_32x32x16_bf16 v[48:63], v[152:155], v[218:221], v[48:63]
	ds_read_b64_tr_b16 v[218:219], v168 offset:0x1400
	ds_read_b64_tr_b16 v[220:221], v168 offset:0x1c00
	v_mfma_f32_32x32x16_bf16 v[48:63], v[208:211], v[224:227], v[48:63]
	ds_read_b64_tr_b16 v[224:225], v168 offset:0x2400
	ds_read_b64_tr_b16 v[226:227], v168 offset:0x2c00
	v_mfma_f32_32x32x16_bf16 v[48:63], v[214:217], v[238:241], v[48:63]
	ds_read_b64_tr_b16 v[238:239], v168 offset:0x3400
	ds_read_b64_tr_b16 v[240:241], v168 offset:0x3c00
	s_waitcnt lgkmcnt(0)
; #define SWRITE(b) do { *(bf16x8*)(V_lds + (b) * SHM_V + vst0) = vs0; *(bf16x8*)(V_lds + (b) * SHM_V + vst1) = vs1; const int kc = sc * 2; \
;     *(bf16x8*)(K_lds + (b) * SHM_K + KSWZ(sr, kc)) = ks0; *(bf16x8*)(K_lds + (b) * SHM_K + KSWZ(32 + sr, kc)) = ks1; \
;     *(bf16x8*)(R_lds + (b) * SHM_R + RSWZ(rr, rc * 2)) = rs0; } while (0)
; #define SWAIT() asm volatile("s_waitcnt vmcnt(0)" ::: "memory")
; #define RESC(a) do { if (__any((a) < 1.f)) { if (hi == 0) al_l[r32] = (a); asm volatile("s_waitcnt lgkmcnt(0)" ::: "memory"); \
;     _Pragma("unroll") for (int d = 0; d < 4; ++d) _Pragma("unroll") for (int r = 0; r < 16; ++r) o[d][r] *= al_l[crow(r, hi)]; } } while (0)
; __device__ __forceinline__ void partialSM(f32x16& p0, f32x16& p1, float& m_reg, float& mn, float& alpha) {
;     constexpr float C = SCALE * 1.4426950408889634f;
;     float pmax = p0[0];
; #pragma unroll
;     for (int r = 1; r < 16; ++r) pmax = fmaxf(pmax, p0[r]);
; #pragma unroll
;     for (int r = 0; r < 16; ++r) pmax = fmaxf(pmax, p1[r]);
;     { auto rr = __builtin_amdgcn_permlane32_swap(__float_as_uint(pmax), __float_as_uint(pmax), false, false);
;       pmax = fmaxf(__uint_as_float(rr[0]), __uint_as_float(rr[1])); }
;     if (__builtin_expect(__all(pmax - m_reg <= THR / SCALE), 1)) { mn = m_reg; alpha = 1.f; }
;     else { mn = fmaxf(m_reg, pmax); alpha = __builtin_amdgcn_exp2f((m_reg - mn) * C); m_reg = mn; }
;     const float mnC = -mn * C;
; #pragma unroll
;     for (int r = 0; r < 16; ++r) p0[r] = fmaf(p0[r], C, mnC);
; #pragma unroll
;     for (int r = 0; r < 16; ++r) p1[r] = fmaf(p1[r], C, mnC);
; #pragma unroll
;     for (int r = 0; r < 16; ++r) p0[r] = __builtin_amdgcn_exp2f(p0[r]);
; }
; __device__ __forceinline__ void attn_body(const bf16_t* __restrict__ Qb, const bf16_t* __restrict__ Kh, const bf16_t* __restrict__ Vh, const bf16_t* __restrict__ Rh,
;                                           bf16_t* __restrict__ Zb, int seq, char* lds, int wv, bool nowrite) {
;     ...
;         pv_d0(o, vb0 + SHM_V, pa0, pa1, pa2, pa3); partialSM(pA0, pA1, m_reg, mnA, alA);
;         __syncthreads(); SWAIT(); SWRITE(1);
;         RESC(alA); __syncthreads();
	v_mfma_f32_32x32x16_bf16 v[32:47], v[148:151], v[160:163], v[32:47]
	ds_read_b64_tr_b16 v[160:161], v168 offset:0x600
	ds_read_b64_tr_b16 v[162:163], v168 offset:0xe00
	v_mfma_f32_32x32x16_bf16 v[32:47], v[152:155], v[218:221], v[32:47]
	ds_read_b64_tr_b16 v[218:219], v168 offset:0x1600
	ds_read_b64_tr_b16 v[220:221], v168 offset:0x1e00
	v_mfma_f32_32x32x16_bf16 v[32:47], v[208:211], v[224:227], v[32:47]
	ds_read_b64_tr_b16 v[224:225], v168 offset:0x2600
	ds_read_b64_tr_b16 v[226:227], v168 offset:0x2e00
	v_mfma_f32_32x32x16_bf16 v[32:47], v[214:217], v[238:241], v[32:47]
	ds_read_b64_tr_b16 v[238:239], v168 offset:0x3600
	ds_read_b64_tr_b16 v[240:241], v168 offset:0x3e00
	s_waitcnt lgkmcnt(0)
	v_mfma_f32_32x32x16_bf16 v[16:31], v[148:151], v[160:163], v[16:31]
	v_max_f32_e32 v148, v81, v81
	v_max_f32_e32 v149, v80, v80
	v_max_f32_e32 v148, v149, v148
	v_max3_f32 v148, v148, v82, v83
	v_max3_f32 v148, v148, v84, v85
	v_max3_f32 v148, v148, v86, v87
	v_max3_f32 v148, v148, v88, v89
	v_max3_f32 v148, v148, v90, v91
	v_max3_f32 v148, v148, v92, v93
	v_mfma_f32_32x32x16_bf16 v[16:31], v[152:155], v[218:221], v[16:31]
	v_max3_f32 v148, v148, v94, v95
	v_max3_f32 v148, v148, v64, v65
	v_max3_f32 v148, v148, v66, v67
	v_max3_f32 v148, v148, v68, v69
	v_max3_f32 v148, v148, v70, v71
	v_max3_f32 v148, v148, v72, v73
	v_max3_f32 v148, v148, v74, v75
	v_max3_f32 v148, v148, v76, v77
	v_mfma_f32_32x32x16_bf16 v[16:31], v[208:211], v[224:227], v[16:31]
	v_max3_f32 v148, v148, v78, v79
	v_mov_b32_e32 v149, v148
	s_nop 1
	v_permlane32_swap_b32_e32 v148, v149
	v_max_f32_e32 v149, v149, v149
	v_max_f32_e32 v148, v148, v148
	v_max_f32_e32 v148, v148, v149
	v_sub_f32_e32 v149, v148, v197
	v_cmp_ge_f32_e32 vcc, s88, v149
	v_max_f32_e32 v149, v197, v197
	v_max_f32_e32 v149, v149, v148
	v_mfma_f32_32x32x16_bf16 v[16:31], v[214:217], v[238:241], v[16:31]
	v_sub_f32_e32 v148, v197, v149
	v_mul_f32_e32 v148, 0x3dd53b94, v148
	v_exp_f32_e32 v148, v148
	s_cmp_eq_u64 vcc, exec
	s_cselect_b64 s[8:9], -1, 0
	s_waitcnt vmcnt(0)
	v_cndmask_b32_e64 v148, v148, 1.0, s[8:9]
	v_cmp_gt_f32_e32 vcc, 1.0, v148
	ds_write_b128 v170, v[128:131]
	ds_write_b128 v171, v[132:135]
	ds_write_b128 v172, v[136:139] offset:49152
	ds_write_b128 v173, v[140:143] offset:49152
	ds_write_b128 v196, v[144:147]
	s_cbranch_vccz .LBB0_616
	s_and_saveexec_b64 s[10:11], s[6:7]
	ds_write_b32 v166, v148 offset:128
	s_or_b64 exec, exec, s[10:11]
	s_waitcnt lgkmcnt(0)
	v_add_u32_e32 v140, s1, v212
	ds_read_b128 v[128:131], v140 offset:224
	ds_read_b128 v[132:135], v140 offset:192
	ds_read_b128 v[136:139], v140 offset:160
	ds_read_b128 v[140:143], v140 offset:128
	s_waitcnt lgkmcnt(3)
	v_pk_mul_f32 v[12:13], v[12:13], v[128:129]
	s_waitcnt lgkmcnt(2)
	v_pk_mul_f32 v[8:9], v[8:9], v[132:133]
	s_waitcnt lgkmcnt(1)
	v_pk_mul_f32 v[4:5], v[4:5], v[136:137]
	v_pk_mul_f32 v[14:15], v[14:15], v[130:131]
	v_pk_mul_f32 v[10:11], v[10:11], v[134:135]
	v_pk_mul_f32 v[6:7], v[6:7], v[138:139]
	s_waitcnt lgkmcnt(0)
	v_pk_mul_f32 v[2:3], v[2:3], v[142:143]
	v_pk_mul_f32 v[0:1], v[0:1], v[140:141]
	v_pk_mul_f32 v[60:61], v[60:61], v[128:129]
	v_pk_mul_f32 v[56:57], v[56:57], v[132:133]
	v_pk_mul_f32 v[52:53], v[52:53], v[136:137]
	v_pk_mul_f32 v[62:63], v[62:63], v[130:131]
	v_pk_mul_f32 v[58:59], v[58:59], v[134:135]
	v_pk_mul_f32 v[54:55], v[54:55], v[138:139]
	v_pk_mul_f32 v[50:51], v[50:51], v[142:143]
	v_pk_mul_f32 v[48:49], v[48:49], v[140:141]
	v_pk_mul_f32 v[44:45], v[44:45], v[128:129]
	v_pk_mul_f32 v[40:41], v[40:41], v[132:133]
	v_pk_mul_f32 v[36:37], v[36:37], v[136:137]
	v_pk_mul_f32 v[46:47], v[46:47], v[130:131]
	v_pk_mul_f32 v[42:43], v[42:43], v[134:135]
	v_pk_mul_f32 v[38:39], v[38:39], v[138:139]
	v_pk_mul_f32 v[34:35], v[34:35], v[142:143]
	v_pk_mul_f32 v[32:33], v[32:33], v[140:141]
	v_pk_mul_f32 v[28:29], v[28:29], v[128:129]
	v_pk_mul_f32 v[24:25], v[24:25], v[132:133]
	v_pk_mul_f32 v[20:21], v[20:21], v[136:137]
	v_pk_mul_f32 v[30:31], v[30:31], v[130:131]
	v_pk_mul_f32 v[26:27], v[26:27], v[134:135]
	v_pk_mul_f32 v[22:23], v[22:23], v[138:139]
	v_pk_mul_f32 v[18:19], v[18:19], v[142:143]
	v_pk_mul_f32 v[16:17], v[16:17], v[140:141]
.LBB0_616:
	v_cndmask_b32_e64 v197, v149, v197, s[8:9]
	v_mul_f32_e32 v134, 0xbdd53b94, v197
	v_mov_b32_e32 v135, v134
	v_fmamk_f32 v80, v80, 0x3dd53b94, v134
	v_fmamk_f32 v81, v81, 0x3dd53b94, v134
	v_fmamk_f32 v82, v82, 0x3dd53b94, v134
	v_fmamk_f32 v83, v83, 0x3dd53b94, v134
	v_fmamk_f32 v84, v84, 0x3dd53b94, v134
	v_fmamk_f32 v85, v85, 0x3dd53b94, v134
	v_fmamk_f32 v86, v86, 0x3dd53b94, v134
	v_fmamk_f32 v87, v87, 0x3dd53b94, v134
	v_fmamk_f32 v88, v88, 0x3dd53b94, v134
	v_fmamk_f32 v89, v89, 0x3dd53b94, v134
	v_fmamk_f32 v90, v90, 0x3dd53b94, v134
	v_fmamk_f32 v91, v91, 0x3dd53b94, v134
	v_fmamk_f32 v92, v92, 0x3dd53b94, v134
	v_fmamk_f32 v93, v93, 0x3dd53b94, v134
	v_fmamk_f32 v94, v94, 0x3dd53b94, v134
	v_fmac_f32_e32 v135, 0x3dd53b94, v95
	v_exp_f32_e32 v162, v80
	v_exp_f32_e32 v205, v81
	v_exp_f32_e32 v149, v82
	v_exp_f32_e32 v163, v83
	v_exp_f32_e32 v150, v84
	v_exp_f32_e32 v161, v85
	v_exp_f32_e32 v151, v86
	v_exp_f32_e32 v160, v87
	v_exp_f32_e32 v152, v88
	v_exp_f32_e32 v155, v89
	v_exp_f32_e32 v153, v90
	v_exp_f32_e32 v154, v91
	v_exp_f32_e32 v145, v92
	v_exp_f32_e32 v147, v93
	v_exp_f32_e32 v144, v94
	v_exp_f32_e32 v146, v135
	v_pk_fma_f32 v[140:141], v[64:65], s[36:37], v[134:135] op_sel_hi:[1,0,0]
	v_add_f32_e32 v64, v202, v203
	v_fmac_f32_e32 v64, v194, v167
	v_add_f32_e32 v167, v206, v207
	s_add_i32 s3, s3, 2
	v_pk_fma_f32 v[138:139], v[66:67], s[36:37], v[134:135] op_sel_hi:[1,0,0]
	v_pk_fma_f32 v[132:133], v[68:69], s[36:37], v[134:135] op_sel_hi:[1,0,0]
	v_pk_fma_f32 v[130:131], v[70:71], s[36:37], v[134:135] op_sel_hi:[1,0,0]
	v_pk_fma_f32 v[128:129], v[72:73], s[36:37], v[134:135] op_sel_hi:[1,0,0]
	v_pk_fma_f32 v[142:143], v[74:75], s[36:37], v[134:135] op_sel_hi:[1,0,0]
	v_pk_fma_f32 v[136:137], v[76:77], s[36:37], v[134:135] op_sel_hi:[1,0,0]
	v_pk_fma_f32 v[134:135], v[78:79], s[36:37], v[134:135] op_sel_hi:[1,0,0]
	v_fmac_f32_e32 v167, v64, v204
	s_cmp_gt_u32 s3, 28
	s_waitcnt lgkmcnt(0)
	s_barrier
; __device__ __forceinline__ void finishSM(f32x16& p0, f32x16& p1, float alpha, float& l_reg, bf16x8& pa0, bf16x8& pa1, bf16x8& pa2, bf16x8& pa3) {
; #pragma unroll
;     for (int r = 0; r < 16; ++r) p1[r] = __builtin_amdgcn_exp2f(p1[r]);
;     float ps = 0;
; #pragma unroll
;     for (int r = 0; r < 16; ++r) ps += p0[r];
; #pragma unroll
;     for (int r = 0; r < 16; ++r) ps += p1[r];
;     { auto rr = __builtin_amdgcn_permlane32_swap(__float_as_uint(ps), __float_as_uint(ps), false, false);
;       ps = __uint_as_float(rr[0]) + __uint_as_float(rr[1]); }
;     l_reg = l_reg * alpha + ps;
; __device__ __forceinline__ void qkt(f32x16& p0, f32x16& p1, const char* Ks, const char* Rs, const bf16x8* qr, const char* Qp, int r32, int hi) {
;     p0 = f32x16{}; p1 = f32x16{};
; #pragma unroll
;     for (int d0 = 0; d0 < 8; ++d0) { const int cb = (d0 * 16 + hi * 8) * 2;
;         const bf16x8 b0 = *reinterpret_cast<const bf16x8*>(Ks + KSWZ(r32, cb));
;         const bf16x8 b1 = *reinterpret_cast<const bf16x8*>(Ks + KSWZ(32 + r32, cb));
;         p0 = __builtin_amdgcn_mfma_f32_32x32x16_bf16(b0, qr[d0], p0, 0, 0, 0);
;         p1 = __builtin_amdgcn_mfma_f32_32x32x16_bf16(b1, qr[d0], p1, 0, 0, 0); }
; #pragma unroll
;     for (int d0 = 0; d0 < 4; ++d0) { const int cb = (d0 * 16 + hi * 8) * 2;
;         const bf16x8 b0 = *reinterpret_cast<const bf16x8*>(Rs + RSWZ(r32, cb));
;         const bf16x8 b1 = *reinterpret_cast<const bf16x8*>(Rs + RSWZ(32 + r32, cb));
;         const bf16x8 qq = *reinterpret_cast<const bf16x8*>(Qp + RSWZ(r32, cb));
;         p0 = __builtin_amdgcn_mfma_f32_32x32x16_bf16(b0, qq, p0, 0, 0, 0);
;         p1 = __builtin_amdgcn_mfma_f32_32x32x16_bf16(b1, qq, p1, 0, 0, 0); }
; }
	s_cbranch_scc1 .LBB0_618
	v_mov_b32_e32 v194, v148
	ds_read_b128 v[64:67], v174 offset:49152
	ds_read_b128 v[68:71], v174 offset:57344
	ds_read_b128 v[198:201], v180 offset:49152
	ds_read_b128 v[206:209], v180 offset:57344
	s_add_i32 s8, 0, 0x12000
	v_add_f32_e32 v148, 0, v162
	s_waitcnt lgkmcnt(3)
	v_mfma_f32_32x32x16_bf16 v[80:95], v[64:67], v[120:123], 0
	v_add_f32_e32 v148, v205, v148
	v_add_f32_e32 v148, v149, v148
	v_add_f32_e32 v148, v163, v148
	v_add_f32_e32 v148, v150, v148
	v_add_f32_e32 v148, v161, v148
	v_add_f32_e32 v148, v151, v148
	v_add_f32_e32 v148, v160, v148
	s_waitcnt lgkmcnt(2)
	v_mfma_f32_32x32x16_bf16 v[64:79], v[68:71], v[120:123], 0
	v_add_f32_e32 v148, v152, v148
	v_add_f32_e32 v148, v155, v148
	v_add_f32_e32 v148, v153, v148
	v_add_f32_e32 v148, v154, v148
	v_exp_f32_e32 v140, v140
	v_add_f32_e32 v148, v145, v148
	v_exp_f32_e32 v141, v141
	s_waitcnt lgkmcnt(1)
	v_mfma_f32_32x32x16_bf16 v[80:95], v[198:201], v[124:127], v[80:95]
	v_add_f32_e32 v148, v147, v148
	v_exp_f32_e32 v138, v138
	v_add_f32_e32 v148, v144, v148
	v_exp_f32_e32 v139, v139
	v_add_f32_e32 v148, v146, v148
	v_exp_f32_e32 v132, v132
	v_add_f32_e32 v148, v140, v148
	s_waitcnt lgkmcnt(0)
	v_mfma_f32_32x32x16_bf16 v[64:79], v[206:209], v[124:127], v[64:79]
	ds_read_b128 v[198:201], v182 offset:49152
	ds_read_b128 v[206:209], v182 offset:57344
	v_exp_f32_e32 v133, v133
	v_add_f32_e32 v148, v141, v148
	v_exp_f32_e32 v130, v130
	v_add_f32_e32 v148, v138, v148
	v_exp_f32_e32 v131, v131
	v_add_f32_e32 v148, v139, v148
	s_waitcnt lgkmcnt(1)
	v_mfma_f32_32x32x16_bf16 v[80:95], v[198:201], v[116:119], v[80:95]
	v_exp_f32_e32 v128, v128
	v_add_f32_e32 v148, v132, v148
	v_exp_f32_e32 v129, v129
	v_add_f32_e32 v148, v133, v148
	v_exp_f32_e32 v142, v142
	v_add_f32_e32 v148, v130, v148
	v_exp_f32_e32 v143, v143
	s_waitcnt lgkmcnt(0)
	v_mfma_f32_32x32x16_bf16 v[64:79], v[206:209], v[116:119], v[64:79]
	ds_read_b128 v[198:201], v184 offset:49152
	ds_read_b128 v[206:209], v184 offset:57344
	v_add_f32_e32 v148, v131, v148
	v_exp_f32_e32 v136, v136
	v_add_f32_e32 v148, v128, v148
	v_exp_f32_e32 v137, v137
	v_add_f32_e32 v148, v129, v148
	v_exp_f32_e32 v134, v134
	s_waitcnt lgkmcnt(1)
	v_mfma_f32_32x32x16_bf16 v[80:95], v[198:201], v[112:115], v[80:95]
	v_add_f32_e32 v148, v142, v148
	v_exp_f32_e32 v135, v135
	v_add_f32_e32 v148, v143, v148
	v_add_f32_e32 v148, v136, v148
	v_add_f32_e32 v148, v137, v148
	v_add_f32_e32 v148, v134, v148
	s_waitcnt lgkmcnt(0)
	v_mfma_f32_32x32x16_bf16 v[64:79], v[206:209], v[112:115], v[64:79]
	ds_read_b128 v[198:201], v185 offset:49152
	ds_read_b128 v[206:209], v185 offset:57344
	s_waitcnt lgkmcnt(1)
	v_mfma_f32_32x32x16_bf16 v[80:95], v[198:201], v[108:111], v[80:95]
	s_waitcnt lgkmcnt(0)
	v_mfma_f32_32x32x16_bf16 v[64:79], v[206:209], v[108:111], v[64:79]
	ds_read_b128 v[198:201], v183 offset:49152
	ds_read_b128 v[206:209], v183 offset:57344
	s_waitcnt lgkmcnt(1)
	v_mfma_f32_32x32x16_bf16 v[80:95], v[198:201], v[104:107], v[80:95]
	s_waitcnt lgkmcnt(0)
	v_mfma_f32_32x32x16_bf16 v[64:79], v[206:209], v[104:107], v[64:79]
	ds_read_b128 v[198:201], v181 offset:49152
	ds_read_b128 v[206:209], v181 offset:57344
	s_waitcnt lgkmcnt(1)
	v_mfma_f32_32x32x16_bf16 v[80:95], v[198:201], v[100:103], v[80:95]
	s_waitcnt lgkmcnt(0)
	v_mfma_f32_32x32x16_bf16 v[64:79], v[206:209], v[100:103], v[64:79]
	ds_read_b128 v[198:201], v179 offset:49152
	ds_read_b128 v[206:209], v179 offset:57344
	s_waitcnt lgkmcnt(1)
	v_mfma_f32_32x32x16_bf16 v[80:95], v[198:201], v[96:99], v[80:95]
	v_add_u32_e32 v199, s8, v186
	v_add_u32_e32 v198, s8, v188
	s_waitcnt lgkmcnt(0)
	v_mfma_f32_32x32x16_bf16 v[64:79], v[206:209], v[96:99], v[64:79]
	ds_read_b128 v[200:203], v199
	ds_read_b128 v[206:209], v199 offset:4096
	ds_read_b128 v[214:217], v177
	s_waitcnt lgkmcnt(0)
	v_mfma_f32_32x32x16_bf16 v[80:95], v[200:203], v[214:217], v[80:95]
	v_mfma_f32_32x32x16_bf16 v[64:79], v[206:209], v[214:217], v[64:79]
	ds_read_b128 v[200:203], v198
	ds_read_b128 v[206:209], v198 offset:4096
	ds_read_b128 v[214:217], v175
	s_waitcnt lgkmcnt(0)
	v_mfma_f32_32x32x16_bf16 v[80:95], v[200:203], v[214:217], v[80:95]
	v_add_u32_e32 v200, s8, v190
	v_add_u32_e32 v201, s8, v192
	v_add_f32_e32 v202, v135, v148
	v_mov_b32_e32 v203, v202
	s_nop 1
	v_permlane32_swap_b32_e32 v202, v203
	v_mfma_f32_32x32x16_bf16 v[64:79], v[206:209], v[214:217], v[64:79]
	ds_read_b128 v[206:209], v200
	ds_read_b128 v[214:217], v200 offset:4096
	ds_read_b128 v[218:221], v178
	s_waitcnt lgkmcnt(0)
	v_mfma_f32_32x32x16_bf16 v[80:95], v[206:209], v[218:221], v[80:95]
	v_mfma_f32_32x32x16_bf16 v[64:79], v[214:217], v[218:221], v[64:79]
	ds_read_b128 v[206:209], v201
	ds_read_b128 v[214:217], v201 offset:4096
	ds_read_b128 v[218:221], v176
	v_cvt_pk_bf16_f32 v148, v162, v205
	v_cvt_pk_bf16_f32 v149, v149, v163
	v_cvt_pk_bf16_f32 v150, v150, v161
	v_cvt_pk_bf16_f32 v151, v151, v160
	v_cvt_pk_bf16_f32 v152, v152, v155
	v_cvt_pk_bf16_f32 v153, v153, v154
	s_waitcnt lgkmcnt(0)
; #define SBAR() __builtin_amdgcn_sched_barrier(0)
; #define SWRITE(b) do { *(bf16x8*)(V_lds + (b) * SHM_V + vst0) = vs0; *(bf16x8*)(V_lds + (b) * SHM_V + vst1) = vs1; const int kc = sc * 2; \
;     *(bf16x8*)(K_lds + (b) * SHM_K + KSWZ(sr, kc)) = ks0; *(bf16x8*)(K_lds + (b) * SHM_K + KSWZ(32 + sr, kc)) = ks1; \
;     *(bf16x8*)(R_lds + (b) * SHM_R + RSWZ(rr, rc * 2)) = rs0; } while (0)
; #define SWAIT() asm volatile("s_waitcnt vmcnt(0)" ::: "memory")
; template <int D0> __device__ __forceinline__ void pv_one(f32x16& od, int vb, bf16x8 pa0, bf16x8 pa1, bf16x8 pa2, bf16x8 pa3) {
;     const s16x4 l0 = tr_read<v_rd_off(D0, 0, 0)>(vb), h0 = tr_read<v_rd_off(D0, 0, 1)>(vb), l1 = tr_read<v_rd_off(D0, 1, 0)>(vb), h1 = tr_read<v_rd_off(D0, 1, 1)>(vb);
;     const s16x4 l2 = tr_read<v_rd_off(D0, 2, 0)>(vb), h2 = tr_read<v_rd_off(D0, 2, 1)>(vb), l3 = tr_read<v_rd_off(D0, 3, 0)>(vb), h3 = tr_read<v_rd_off(D0, 3, 1)>(vb);
;     asm volatile("s_waitcnt lgkmcnt(0)" ::: "memory"); SBAR();
;     ...
;     od = __builtin_amdgcn_mfma_f32_32x32x16_bf16(pa0, PK(l0, h0), od, 0, 0, 0);
;     od = __builtin_amdgcn_mfma_f32_32x32x16_bf16(pa1, PK(l1, h1), od, 0, 0, 0);
;     od = __builtin_amdgcn_mfma_f32_32x32x16_bf16(pa2, PK(l2, h2), od, 0, 0, 0);
;     od = __builtin_amdgcn_mfma_f32_32x32x16_bf16(pa3, PK(l3, h3), od, 0, 0, 0);
;     ...
; }
; __device__ __forceinline__ void pv_d0(f32x16* o, int vb, bf16x8 pa0, bf16x8 pa1, bf16x8 pa2, bf16x8 pa3) {
;     pv_one<0>(o[0], vb, pa0, pa1, pa2, pa3); pv_one<1>(o[1], vb, pa0, pa1, pa2, pa3); pv_one<2>(o[2], vb, pa0, pa1, pa2, pa3); pv_one<3>(o[3], vb, pa0, pa1, pa2, pa3);
; __device__ __forceinline__ void attn_body(const bf16_t* __restrict__ Qb, const bf16_t* __restrict__ Kh, const bf16_t* __restrict__ Vh, const bf16_t* __restrict__ Rh,
;                                           bf16_t* __restrict__ Zb, int seq, char* lds, int wv, bool nowrite) {
;     ...
;     for (int j = 1; j + 1 < NT; j += 2) {
;         SBAR(); qkt(pB0, pB1, K_lds + SHM_K, R_lds + SHM_R, qr, Qp, r32, hi);
;         finishSM(pA0, pA1, alA, l_reg, pa0, pa1, pa2, pa3); SBAR();
;         SLOAD((j + 1) * KVBLK); SBAR();
;         pv_d0(o, vb0, pa0, pa1, pa2, pa3); partialSM(pB0, pB1, m_reg, mnB, alB);
;         __syncthreads(); SWAIT(); SWRITE(0);
	v_mfma_f32_32x32x16_bf16 v[80:95], v[206:209], v[218:221], v[80:95]
	v_cvt_pk_bf16_f32 v154, v145, v147
	v_cvt_pk_bf16_f32 v155, v144, v146
	v_cvt_pk_bf16_f32 v204, v140, v141
	v_cvt_pk_bf16_f32 v205, v138, v139
	v_cvt_pk_bf16_f32 v206, v132, v133
	v_permlane32_swap_b32_e32 v148, v150
	v_mfma_f32_32x32x16_bf16 v[64:79], v[214:217], v[218:221], v[64:79]
	v_cvt_pk_bf16_f32 v207, v130, v131
	v_permlane32_swap_b32_e32 v204, v206
	v_cvt_pk_bf16_f32 v208, v128, v129
	v_cvt_pk_bf16_f32 v209, v142, v143
	v_cvt_pk_bf16_f32 v210, v136, v137
	v_cvt_pk_bf16_f32 v211, v134, v135
	v_permlane32_swap_b32_e32 v149, v151
	v_permlane32_swap_b32_e32 v152, v154
	v_permlane32_swap_b32_e32 v153, v155
	v_permlane32_swap_b32_e32 v205, v207
	v_permlane32_swap_b32_e32 v208, v210
	v_permlane32_swap_b32_e32 v209, v211
	global_load_dwordx4 v[128:131], v242, s[44:45]
	global_load_dwordx4 v[132:135], v243, s[44:45]
	global_load_dwordx4 v[136:139], v244, s[44:45]
	global_load_dwordx4 v[140:143], v245, s[44:45]
	global_load_dwordx4 v[144:147], v246, s[44:45]
	v_add_u32_e32 v242, 0x40000, v242
	v_add_u32_e32 v243, 0x40000, v243
	v_add_u32_e32 v244, 0x40000, v244
	v_add_u32_e32 v245, 0x40000, v245
	v_add_u32_e32 v246, 0x2000, v246
	ds_read_b64_tr_b16 v[214:215], v247 offset:0
	ds_read_b64_tr_b16 v[216:217], v247 offset:0x800
	ds_read_b64_tr_b16 v[218:219], v247 offset:0x1000
	ds_read_b64_tr_b16 v[220:221], v247 offset:0x1800
	ds_read_b64_tr_b16 v[224:225], v247 offset:0x2000
	ds_read_b64_tr_b16 v[226:227], v247 offset:0x2800
	ds_read_b64_tr_b16 v[238:239], v247 offset:0x3000
	ds_read_b64_tr_b16 v[240:241], v247 offset:0x3800
	s_waitcnt lgkmcnt(0)
	s_nop 0
	v_mfma_f32_32x32x16_bf16 v[0:15], v[148:151], v[214:217], v[0:15]
	ds_read_b64_tr_b16 v[214:215], v247 offset:0x200
	ds_read_b64_tr_b16 v[216:217], v247 offset:0xa00
	v_mfma_f32_32x32x16_bf16 v[0:15], v[152:155], v[218:221], v[0:15]
	ds_read_b64_tr_b16 v[218:219], v247 offset:0x1200
	ds_read_b64_tr_b16 v[220:221], v247 offset:0x1a00
	v_mfma_f32_32x32x16_bf16 v[0:15], v[204:207], v[224:227], v[0:15]
	ds_read_b64_tr_b16 v[224:225], v247 offset:0x2200
	ds_read_b64_tr_b16 v[226:227], v247 offset:0x2a00
	v_mfma_f32_32x32x16_bf16 v[0:15], v[208:211], v[238:241], v[0:15]
	ds_read_b64_tr_b16 v[238:239], v247 offset:0x3200
	ds_read_b64_tr_b16 v[240:241], v247 offset:0x3a00
	s_waitcnt lgkmcnt(0)
	v_mfma_f32_32x32x16_bf16 v[48:63], v[148:151], v[214:217], v[48:63]
	ds_read_b64_tr_b16 v[214:215], v247 offset:0x400
	ds_read_b64_tr_b16 v[216:217], v247 offset:0xc00
	v_mfma_f32_32x32x16_bf16 v[48:63], v[152:155], v[218:221], v[48:63]
	ds_read_b64_tr_b16 v[218:219], v247 offset:0x1400
	ds_read_b64_tr_b16 v[220:221], v247 offset:0x1c00
	v_mfma_f32_32x32x16_bf16 v[48:63], v[204:207], v[224:227], v[48:63]
	ds_read_b64_tr_b16 v[224:225], v247 offset:0x2400
	ds_read_b64_tr_b16 v[226:227], v247 offset:0x2c00
	v_mfma_f32_32x32x16_bf16 v[48:63], v[208:211], v[238:241], v[48:63]
	ds_read_b64_tr_b16 v[238:239], v247 offset:0x3400
	ds_read_b64_tr_b16 v[240:241], v247 offset:0x3c00
	s_waitcnt lgkmcnt(0)
	v_mfma_f32_32x32x16_bf16 v[32:47], v[148:151], v[214:217], v[32:47]
	ds_read_b64_tr_b16 v[214:215], v247 offset:0x600
	ds_read_b64_tr_b16 v[216:217], v247 offset:0xe00
	v_mfma_f32_32x32x16_bf16 v[32:47], v[152:155], v[218:221], v[32:47]
	ds_read_b64_tr_b16 v[218:219], v247 offset:0x1600
	ds_read_b64_tr_b16 v[220:221], v247 offset:0x1e00
	v_mfma_f32_32x32x16_bf16 v[32:47], v[204:207], v[224:227], v[32:47]
	ds_read_b64_tr_b16 v[224:225], v247 offset:0x2600
	ds_read_b64_tr_b16 v[226:227], v247 offset:0x2e00
	v_mfma_f32_32x32x16_bf16 v[32:47], v[208:211], v[238:241], v[32:47]
	ds_read_b64_tr_b16 v[238:239], v247 offset:0x3600
	ds_read_b64_tr_b16 v[240:241], v247 offset:0x3e00
	s_waitcnt lgkmcnt(0)
	v_mfma_f32_32x32x16_bf16 v[16:31], v[148:151], v[214:217], v[16:31]
	v_max_f32_e32 v148, v81, v81
	v_max_f32_e32 v149, v80, v80
	v_max_f32_e32 v148, v149, v148
	v_max3_f32 v148, v148, v82, v83
	v_max3_f32 v148, v148, v84, v85
	v_max3_f32 v148, v148, v86, v87
	v_max3_f32 v148, v148, v88, v89
	v_max3_f32 v148, v148, v90, v91
	v_max3_f32 v148, v148, v92, v93
	v_mfma_f32_32x32x16_bf16 v[16:31], v[152:155], v[218:221], v[16:31]
	v_max3_f32 v148, v148, v94, v95
	v_max3_f32 v148, v148, v64, v65
	v_max3_f32 v148, v148, v66, v67
	v_max3_f32 v148, v148, v68, v69
	v_max3_f32 v148, v148, v70, v71
	v_max3_f32 v148, v148, v72, v73
	v_max3_f32 v148, v148, v74, v75
	v_max3_f32 v148, v148, v76, v77
	v_mfma_f32_32x32x16_bf16 v[16:31], v[204:207], v[224:227], v[16:31]
	v_max3_f32 v148, v148, v78, v79
	v_mov_b32_e32 v149, v148
	s_nop 1
	v_permlane32_swap_b32_e32 v148, v149
	v_max_f32_e32 v149, v149, v149
	v_max_f32_e32 v148, v148, v148
	v_max_f32_e32 v148, v148, v149
	v_sub_f32_e32 v149, v148, v197
	v_cmp_ge_f32_e32 vcc, s88, v149
	v_max_f32_e32 v149, v197, v197
	v_max_f32_e32 v148, v149, v148
	v_mfma_f32_32x32x16_bf16 v[16:31], v[208:211], v[238:241], v[16:31]
	v_sub_f32_e32 v149, v197, v148
	v_mul_f32_e32 v149, 0x3dd53b94, v149
	v_exp_f32_e32 v149, v149
	s_cmp_eq_u64 vcc, exec
	s_cselect_b64 s[8:9], -1, 0
	s_waitcnt vmcnt(0)
	v_cndmask_b32_e64 v204, v149, 1.0, s[8:9]
	ds_write_b128 v170, v[128:131] offset:16384
	ds_write_b128 v171, v[132:135] offset:16384
	ds_write_b128 v172, v[136:139] offset:32768
	ds_write_b128 v173, v[140:143] offset:32768
	v_add_u32_e32 v128, 0x10000, v195
	v_cmp_gt_f32_e32 vcc, 1.0, v204
	ds_write_b128 v128, v[144:147]
	s_cbranch_vccz .Latt_u1_612
; __device__ __forceinline__ void partialSM(f32x16& p0, f32x16& p1, float& m_reg, float& mn, float& alpha) {
;     ...
;     if (__builtin_expect(__all(pmax - m_reg <= THR / SCALE), 1)) { mn = m_reg; alpha = 1.f; }
;     else { mn = fmaxf(m_reg, pmax); alpha = __builtin_amdgcn_exp2f((m_reg - mn) * C); m_reg = mn; }
;     const float mnC = -mn * C;
; #pragma unroll
;     for (int r = 0; r < 16; ++r) p0[r] = fmaf(p0[r], C, mnC);
; #pragma unroll
;     for (int r = 0; r < 16; ++r) p1[r] = fmaf(p1[r], C, mnC);
; #pragma unroll
;     for (int r = 0; r < 16; ++r) p0[r] = __builtin_amdgcn_exp2f(p0[r]);
	s_and_saveexec_b64 s[10:11], s[6:7]
	ds_write_b32 v166, v204 offset:128
	s_or_b64 exec, exec, s[10:11]
	s_waitcnt lgkmcnt(0)
	v_add_u32_e32 v140, s1, v212
	ds_read_b128 v[128:131], v140 offset:224
	ds_read_b128 v[132:135], v140 offset:192
	ds_read_b128 v[136:139], v140 offset:160
	ds_read_b128 v[140:143], v140 offset:128
	s_waitcnt lgkmcnt(3)
	v_pk_mul_f32 v[12:13], v[12:13], v[128:129]
	s_waitcnt lgkmcnt(2)
	v_pk_mul_f32 v[8:9], v[8:9], v[132:133]
	s_waitcnt lgkmcnt(1)
	v_pk_mul_f32 v[4:5], v[4:5], v[136:137]
	v_pk_mul_f32 v[14:15], v[14:15], v[130:131]
	v_pk_mul_f32 v[10:11], v[10:11], v[134:135]
	v_pk_mul_f32 v[6:7], v[6:7], v[138:139]
	s_waitcnt lgkmcnt(0)
	v_pk_mul_f32 v[2:3], v[2:3], v[142:143]
	v_pk_mul_f32 v[0:1], v[0:1], v[140:141]
	v_pk_mul_f32 v[60:61], v[60:61], v[128:129]
	v_pk_mul_f32 v[56:57], v[56:57], v[132:133]
	v_pk_mul_f32 v[52:53], v[52:53], v[136:137]
	v_pk_mul_f32 v[62:63], v[62:63], v[130:131]
	v_pk_mul_f32 v[58:59], v[58:59], v[134:135]
	v_pk_mul_f32 v[54:55], v[54:55], v[138:139]
	v_pk_mul_f32 v[50:51], v[50:51], v[142:143]
	v_pk_mul_f32 v[48:49], v[48:49], v[140:141]
	v_pk_mul_f32 v[44:45], v[44:45], v[128:129]
	v_pk_mul_f32 v[40:41], v[40:41], v[132:133]
	v_pk_mul_f32 v[36:37], v[36:37], v[136:137]
	v_pk_mul_f32 v[46:47], v[46:47], v[130:131]
	v_pk_mul_f32 v[42:43], v[42:43], v[134:135]
	v_pk_mul_f32 v[38:39], v[38:39], v[138:139]
	v_pk_mul_f32 v[34:35], v[34:35], v[142:143]
	v_pk_mul_f32 v[32:33], v[32:33], v[140:141]
	v_pk_mul_f32 v[28:29], v[28:29], v[128:129]
	v_pk_mul_f32 v[24:25], v[24:25], v[132:133]
	v_pk_mul_f32 v[20:21], v[20:21], v[136:137]
	v_pk_mul_f32 v[30:31], v[30:31], v[130:131]
	v_pk_mul_f32 v[26:27], v[26:27], v[134:135]
	v_pk_mul_f32 v[22:23], v[22:23], v[138:139]
	v_pk_mul_f32 v[18:19], v[18:19], v[142:143]
	v_pk_mul_f32 v[16:17], v[16:17], v[140:141]
.Latt_u1_612:
	v_cndmask_b32_e64 v197, v148, v197, s[8:9]
	v_mul_f32_e32 v144, 0xbdd53b94, v197
	v_fmamk_f32 v80, v80, 0x3dd53b94, v144
	v_fmamk_f32 v81, v81, 0x3dd53b94, v144
	v_fmamk_f32 v82, v82, 0x3dd53b94, v144
	v_fmamk_f32 v83, v83, 0x3dd53b94, v144
	v_fmamk_f32 v84, v84, 0x3dd53b94, v144
	v_fmamk_f32 v85, v85, 0x3dd53b94, v144
	v_fmamk_f32 v86, v86, 0x3dd53b94, v144
	v_fmamk_f32 v87, v87, 0x3dd53b94, v144
	v_fmamk_f32 v88, v88, 0x3dd53b94, v144
	v_fmamk_f32 v89, v89, 0x3dd53b94, v144
	v_fmamk_f32 v90, v90, 0x3dd53b94, v144
	v_fmamk_f32 v91, v91, 0x3dd53b94, v144
	v_fmamk_f32 v92, v92, 0x3dd53b94, v144
	v_fmamk_f32 v93, v93, 0x3dd53b94, v144
	v_fmamk_f32 v94, v94, 0x3dd53b94, v144
	v_fmamk_f32 v95, v95, 0x3dd53b94, v144
	v_fmamk_f32 v206, v68, 0x3dd53b94, v144
	v_fmamk_f32 v148, v71, 0x3dd53b94, v144
	v_fmamk_f32 v149, v72, 0x3dd53b94, v144
	v_fmamk_f32 v207, v77, 0x3dd53b94, v144
	v_fmamk_f32 v153, v64, 0x3dd53b94, v144
	v_fmamk_f32 v154, v65, 0x3dd53b94, v144
	v_fmamk_f32 v155, v66, 0x3dd53b94, v144
	v_fmamk_f32 v205, v67, 0x3dd53b94, v144
	v_fmamk_f32 v146, v69, 0x3dd53b94, v144
	v_fmamk_f32 v147, v70, 0x3dd53b94, v144
	v_fmamk_f32 v150, v73, 0x3dd53b94, v144
	v_fmamk_f32 v151, v74, 0x3dd53b94, v144
	v_fmamk_f32 v152, v75, 0x3dd53b94, v144
	v_fmamk_f32 v145, v76, 0x3dd53b94, v144
	v_exp_f32_e32 v141, v80
	v_exp_f32_e32 v143, v81
	v_exp_f32_e32 v139, v82
	v_exp_f32_e32 v142, v83
	v_exp_f32_e32 v138, v84
	v_exp_f32_e32 v140, v85
	v_exp_f32_e32 v136, v86
	v_exp_f32_e32 v137, v87
	v_exp_f32_e32 v133, v88
	v_exp_f32_e32 v135, v89
	v_exp_f32_e32 v132, v90
	v_exp_f32_e32 v134, v91
	v_exp_f32_e32 v129, v92
	v_exp_f32_e32 v131, v93
	v_exp_f32_e32 v128, v94
	v_exp_f32_e32 v130, v95
	v_fmamk_f32 v208, v78, 0x3dd53b94, v144
	v_fmac_f32_e32 v144, 0x3dd53b94, v79
	s_waitcnt lgkmcnt(0)
	s_barrier
	ds_read_b128 v[64:67], v174 offset:32768
	ds_read_b128 v[68:71], v174 offset:40960
	ds_read_b128 v[214:217], v180 offset:32768
	ds_read_b128 v[218:221], v180 offset:40960
	v_exp_f32_e32 v209, v153
	v_exp_f32_e32 v210, v154
	s_waitcnt lgkmcnt(3)
	v_mfma_f32_32x32x16_bf16 v[80:95], v[64:67], v[120:123], 0
	v_exp_f32_e32 v211, v155
	v_exp_f32_e32 v205, v205
	v_exp_f32_e32 v146, v146
	v_exp_f32_e32 v147, v147
	v_exp_f32_e32 v145, v145
	v_exp_f32_e32 v144, v144
	s_waitcnt lgkmcnt(2)
	v_mfma_f32_32x32x16_bf16 v[64:79], v[68:71], v[120:123], 0
	s_waitcnt lgkmcnt(1)
	v_mfma_f32_32x32x16_bf16 v[80:95], v[214:217], v[124:127], v[80:95]
	s_waitcnt lgkmcnt(0)
	v_mfma_f32_32x32x16_bf16 v[64:79], v[218:221], v[124:127], v[64:79]
	ds_read_b128 v[214:217], v182 offset:32768
	ds_read_b128 v[218:221], v182 offset:40960
	s_waitcnt lgkmcnt(1)
	v_mfma_f32_32x32x16_bf16 v[80:95], v[214:217], v[116:119], v[80:95]
	s_waitcnt lgkmcnt(0)
	v_mfma_f32_32x32x16_bf16 v[64:79], v[218:221], v[116:119], v[64:79]
	ds_read_b128 v[214:217], v184 offset:32768
	ds_read_b128 v[218:221], v184 offset:40960
	s_waitcnt lgkmcnt(1)
	v_mfma_f32_32x32x16_bf16 v[80:95], v[214:217], v[112:115], v[80:95]
	s_waitcnt lgkmcnt(0)
	v_mfma_f32_32x32x16_bf16 v[64:79], v[218:221], v[112:115], v[64:79]
	ds_read_b128 v[214:217], v185 offset:32768
	ds_read_b128 v[218:221], v185 offset:40960
	s_waitcnt lgkmcnt(1)
	v_mfma_f32_32x32x16_bf16 v[80:95], v[214:217], v[108:111], v[80:95]
	s_waitcnt lgkmcnt(0)
	v_mfma_f32_32x32x16_bf16 v[64:79], v[218:221], v[108:111], v[64:79]
	ds_read_b128 v[214:217], v183 offset:32768
	ds_read_b128 v[218:221], v183 offset:40960
	s_waitcnt lgkmcnt(1)
	v_mfma_f32_32x32x16_bf16 v[80:95], v[214:217], v[104:107], v[80:95]
	s_waitcnt lgkmcnt(0)
	v_mfma_f32_32x32x16_bf16 v[64:79], v[218:221], v[104:107], v[64:79]
	ds_read_b128 v[214:217], v181 offset:32768
	ds_read_b128 v[218:221], v181 offset:40960
	s_waitcnt lgkmcnt(1)
	v_mfma_f32_32x32x16_bf16 v[80:95], v[214:217], v[100:103], v[80:95]
	s_waitcnt lgkmcnt(0)
; #define SBAR() __builtin_amdgcn_sched_barrier(0)
; __device__ __forceinline__ void finishSM(f32x16& p0, f32x16& p1, float alpha, float& l_reg, bf16x8& pa0, bf16x8& pa1, bf16x8& pa2, bf16x8& pa3) {
; #pragma unroll
;     for (int r = 0; r < 16; ++r) p1[r] = __builtin_amdgcn_exp2f(p1[r]);
;     float ps = 0;
; #pragma unroll
;     for (int r = 0; r < 16; ++r) ps += p0[r];
; #pragma unroll
;     for (int r = 0; r < 16; ++r) ps += p1[r];
;     { auto rr = __builtin_amdgcn_permlane32_swap(__float_as_uint(ps), __float_as_uint(ps), false, false);
;       ps = __uint_as_float(rr[0]) + __uint_as_float(rr[1]); }
;     l_reg = l_reg * alpha + ps;
;     ...
;     PK4(p0, 0, pa0); PK4(p0, 8, pa1); PK4(p1, 0, pa2); PK4(p1, 8, pa3);
; __device__ __forceinline__ void attn_body(const bf16_t* __restrict__ Qb, const bf16_t* __restrict__ Kh, const bf16_t* __restrict__ Vh, const bf16_t* __restrict__ Rh,
;                                           bf16_t* __restrict__ Zb, int seq, char* lds, int wv, bool nowrite) {
;     ...
;         SBAR(); qkt(pA0, pA1, K_lds, R_lds, qr, Qp, r32, hi);
;         finishSM(pB0, pB1, alB, l_reg, pa0, pa1, pa2, pa3); SBAR();
;         SLOAD((j + 2) * KVBLK); SBAR();
;         pv_d0(o, vb0 + SHM_V, pa0, pa1, pa2, pa3); partialSM(pA0, pA1, m_reg, mnA, alA);
	v_mfma_f32_32x32x16_bf16 v[64:79], v[218:221], v[100:103], v[64:79]
	ds_read_b128 v[214:217], v179 offset:32768
	ds_read_b128 v[218:221], v179 offset:40960
	s_waitcnt lgkmcnt(1)
	v_mfma_f32_32x32x16_bf16 v[80:95], v[214:217], v[96:99], v[80:95]
	s_waitcnt lgkmcnt(0)
	v_mfma_f32_32x32x16_bf16 v[64:79], v[218:221], v[96:99], v[64:79]
	ds_read_b128 v[214:217], v187
	ds_read_b128 v[218:221], v187 offset:4096
	ds_read_b128 v[224:227], v177
	s_waitcnt lgkmcnt(0)
	v_mfma_f32_32x32x16_bf16 v[80:95], v[214:217], v[224:227], v[80:95]
	v_mfma_f32_32x32x16_bf16 v[64:79], v[218:221], v[224:227], v[64:79]
	ds_read_b128 v[214:217], v189
	ds_read_b128 v[218:221], v189 offset:4096
	ds_read_b128 v[224:227], v175
	s_waitcnt lgkmcnt(0)
	v_mfma_f32_32x32x16_bf16 v[80:95], v[214:217], v[224:227], v[80:95]
	v_mfma_f32_32x32x16_bf16 v[64:79], v[218:221], v[224:227], v[64:79]
	ds_read_b128 v[214:217], v191
	ds_read_b128 v[218:221], v191 offset:4096
	ds_read_b128 v[224:227], v178
	s_waitcnt lgkmcnt(0)
	v_mfma_f32_32x32x16_bf16 v[80:95], v[214:217], v[224:227], v[80:95]
	v_mfma_f32_32x32x16_bf16 v[64:79], v[218:221], v[224:227], v[64:79]
	ds_read_b128 v[214:217], v193
	ds_read_b128 v[218:221], v193 offset:4096
	ds_read_b128 v[224:227], v176
	s_waitcnt lgkmcnt(0)
	v_mfma_f32_32x32x16_bf16 v[80:95], v[214:217], v[224:227], v[80:95]
	v_exp_f32_e32 v215, v148
	v_add_f32_e32 v148, 0, v141
	v_add_f32_e32 v148, v143, v148
	v_add_f32_e32 v148, v139, v148
	v_add_f32_e32 v148, v142, v148
	v_add_f32_e32 v148, v138, v148
	v_add_f32_e32 v148, v140, v148
	v_add_f32_e32 v148, v136, v148
	v_add_f32_e32 v148, v137, v148
	v_add_f32_e32 v148, v133, v148
	v_add_f32_e32 v148, v135, v148
	v_add_f32_e32 v148, v132, v148
	v_add_f32_e32 v148, v134, v148
	v_add_f32_e32 v148, v129, v148
	v_add_f32_e32 v148, v131, v148
	v_add_f32_e32 v148, v128, v148
	v_add_f32_e32 v148, v130, v148
	v_exp_f32_e32 v214, v206
	v_add_f32_e32 v148, v209, v148
	v_add_f32_e32 v148, v210, v148
	v_add_f32_e32 v148, v211, v148
	v_add_f32_e32 v148, v205, v148
	v_exp_f32_e32 v216, v149
	v_add_f32_e32 v148, v214, v148
	v_exp_f32_e32 v217, v150
	v_add_f32_e32 v148, v146, v148
	v_mfma_f32_32x32x16_bf16 v[64:79], v[218:221], v[224:227], v[64:79]
	v_exp_f32_e32 v218, v151
	v_add_f32_e32 v148, v147, v148
	v_exp_f32_e32 v219, v152
	v_add_f32_e32 v148, v215, v148
	v_add_f32_e32 v148, v216, v148
	v_exp_f32_e32 v220, v207
	v_add_f32_e32 v148, v217, v148
	v_exp_f32_e32 v221, v208
	v_add_f32_e32 v148, v218, v148
	v_add_f32_e32 v148, v219, v148
	v_add_f32_e32 v148, v145, v148
	v_add_f32_e32 v148, v220, v148
	v_add_f32_e32 v148, v221, v148
	v_add_f32_e32 v206, v144, v148
	v_mov_b32_e32 v207, v206
	v_cvt_pk_bf16_f32 v148, v141, v143
	v_cvt_pk_bf16_f32 v149, v139, v142
	v_cvt_pk_bf16_f32 v150, v138, v140
	v_cvt_pk_bf16_f32 v151, v136, v137
	s_nop 1
	v_permlane32_swap_b32_e32 v206, v207
	v_permlane32_swap_b32_e32 v148, v150
	v_permlane32_swap_b32_e32 v149, v151
	v_cvt_pk_bf16_f32 v152, v133, v135
	v_cvt_pk_bf16_f32 v153, v132, v134
	v_cvt_pk_bf16_f32 v154, v129, v131
	v_cvt_pk_bf16_f32 v155, v128, v130
	v_cvt_pk_bf16_f32 v208, v209, v210
	v_cvt_pk_bf16_f32 v209, v211, v205
	v_cvt_pk_bf16_f32 v210, v214, v146
	v_cvt_pk_bf16_f32 v211, v147, v215
	v_cvt_pk_bf16_f32 v214, v216, v217
	v_cvt_pk_bf16_f32 v215, v218, v219
	v_cvt_pk_bf16_f32 v216, v145, v220
	v_cvt_pk_bf16_f32 v217, v221, v144
	s_nop 0
	v_permlane32_swap_b32_e32 v152, v154
	v_permlane32_swap_b32_e32 v153, v155
	v_permlane32_swap_b32_e32 v208, v210
	v_permlane32_swap_b32_e32 v209, v211
	v_permlane32_swap_b32_e32 v214, v216
	v_permlane32_swap_b32_e32 v215, v217
	global_load_dwordx4 v[128:131], v242, s[44:45]
	global_load_dwordx4 v[132:135], v243, s[44:45]
	global_load_dwordx4 v[136:139], v244, s[44:45]
	global_load_dwordx4 v[140:143], v245, s[44:45]
	global_load_dwordx4 v[144:147], v246, s[44:45]
	v_add_u32_e32 v242, 0x40000, v242
	v_add_u32_e32 v243, 0x40000, v243
	v_add_u32_e32 v244, 0x40000, v244
	v_add_u32_e32 v245, 0x40000, v245
	v_add_u32_e32 v246, 0x2000, v246
	ds_read_b64_tr_b16 v[160:161], v169 offset:0
	ds_read_b64_tr_b16 v[162:163], v169 offset:0x800
	ds_read_b64_tr_b16 v[218:219], v169 offset:0x1000
	ds_read_b64_tr_b16 v[220:221], v169 offset:0x1800
	ds_read_b64_tr_b16 v[224:225], v169 offset:0x2000
	ds_read_b64_tr_b16 v[226:227], v169 offset:0x2800
	ds_read_b64_tr_b16 v[238:239], v169 offset:0x3000
	ds_read_b64_tr_b16 v[240:241], v169 offset:0x3800
	s_waitcnt lgkmcnt(0)
	s_nop 0
	v_mfma_f32_32x32x16_bf16 v[0:15], v[148:151], v[160:163], v[0:15]
	ds_read_b64_tr_b16 v[160:161], v169 offset:0x200
	ds_read_b64_tr_b16 v[162:163], v169 offset:0xa00
	v_mfma_f32_32x32x16_bf16 v[0:15], v[152:155], v[218:221], v[0:15]
	ds_read_b64_tr_b16 v[218:219], v169 offset:0x1200
	ds_read_b64_tr_b16 v[220:221], v169 offset:0x1a00
	v_mfma_f32_32x32x16_bf16 v[0:15], v[208:211], v[224:227], v[0:15]
	ds_read_b64_tr_b16 v[224:225], v169 offset:0x2200
	ds_read_b64_tr_b16 v[226:227], v169 offset:0x2a00
	v_mfma_f32_32x32x16_bf16 v[0:15], v[214:217], v[238:241], v[0:15]
	ds_read_b64_tr_b16 v[238:239], v169 offset:0x3200
	ds_read_b64_tr_b16 v[240:241], v169 offset:0x3a00
	s_waitcnt lgkmcnt(0)
	v_mfma_f32_32x32x16_bf16 v[48:63], v[148:151], v[160:163], v[48:63]
	ds_read_b64_tr_b16 v[160:161], v169 offset:0x400
	ds_read_b64_tr_b16 v[162:163], v169 offset:0xc00
	v_mfma_f32_32x32x16_bf16 v[48:63], v[152:155], v[218:221], v[48:63]
	ds_read_b64_tr_b16 v[218:219], v169 offset:0x1400
	ds_read_b64_tr_b16 v[220:221], v169 offset:0x1c00
	v_mfma_f32_32x32x16_bf16 v[48:63], v[208:211], v[224:227], v[48:63]
	ds_read_b64_tr_b16 v[224:225], v169 offset:0x2400
	ds_read_b64_tr_b16 v[226:227], v169 offset:0x2c00
	v_mfma_f32_32x32x16_bf16 v[48:63], v[214:217], v[238:241], v[48:63]
	ds_read_b64_tr_b16 v[238:239], v169 offset:0x3400
	ds_read_b64_tr_b16 v[240:241], v169 offset:0x3c00
	s_waitcnt lgkmcnt(0)
; #define SWRITE(b) do { *(bf16x8*)(V_lds + (b) * SHM_V + vst0) = vs0; *(bf16x8*)(V_lds + (b) * SHM_V + vst1) = vs1; const int kc = sc * 2; \
;     *(bf16x8*)(K_lds + (b) * SHM_K + KSWZ(sr, kc)) = ks0; *(bf16x8*)(K_lds + (b) * SHM_K + KSWZ(32 + sr, kc)) = ks1; \
;     *(bf16x8*)(R_lds + (b) * SHM_R + RSWZ(rr, rc * 2)) = rs0; } while (0)
; #define SWAIT() asm volatile("s_waitcnt vmcnt(0)" ::: "memory")
; #define RESC(a) do { if (__any((a) < 1.f)) { if (hi == 0) al_l[r32] = (a); asm volatile("s_waitcnt lgkmcnt(0)" ::: "memory"); \
;     _Pragma("unroll") for (int d = 0; d < 4; ++d) _Pragma("unroll") for (int r = 0; r < 16; ++r) o[d][r] *= al_l[crow(r, hi)]; } } while (0)
; __device__ __forceinline__ void partialSM(f32x16& p0, f32x16& p1, float& m_reg, float& mn, float& alpha) {
;     constexpr float C = SCALE * 1.4426950408889634f;
;     float pmax = p0[0];
; #pragma unroll
;     for (int r = 1; r < 16; ++r) pmax = fmaxf(pmax, p0[r]);
; #pragma unroll
;     for (int r = 0; r < 16; ++r) pmax = fmaxf(pmax, p1[r]);
;     { auto rr = __builtin_amdgcn_permlane32_swap(__float_as_uint(pmax), __float_as_uint(pmax), false, false);
;       pmax = fmaxf(__uint_as_float(rr[0]), __uint_as_float(rr[1])); }
;     if (__builtin_expect(__all(pmax - m_reg <= THR / SCALE), 1)) { mn = m_reg; alpha = 1.f; }
;     else { mn = fmaxf(m_reg, pmax); alpha = __builtin_amdgcn_exp2f((m_reg - mn) * C); m_reg = mn; }
;     const float mnC = -mn * C;
; #pragma unroll
;     for (int r = 0; r < 16; ++r) p0[r] = fmaf(p0[r], C, mnC);
; #pragma unroll
;     for (int r = 0; r < 16; ++r) p1[r] = fmaf(p1[r], C, mnC);
; #pragma unroll
;     for (int r = 0; r < 16; ++r) p0[r] = __builtin_amdgcn_exp2f(p0[r]);
; }
; __device__ __forceinline__ void attn_body(const bf16_t* __restrict__ Qb, const bf16_t* __restrict__ Kh, const bf16_t* __restrict__ Vh, const bf16_t* __restrict__ Rh,
;                                           bf16_t* __restrict__ Zb, int seq, char* lds, int wv, bool nowrite) {
;     ...
;         pv_d0(o, vb0 + SHM_V, pa0, pa1, pa2, pa3); partialSM(pA0, pA1, m_reg, mnA, alA);
;         __syncthreads(); SWAIT(); SWRITE(1);
;         RESC(alA); __syncthreads();
	v_mfma_f32_32x32x16_bf16 v[32:47], v[148:151], v[160:163], v[32:47]
	ds_read_b64_tr_b16 v[160:161], v169 offset:0x600
	ds_read_b64_tr_b16 v[162:163], v169 offset:0xe00
	v_mfma_f32_32x32x16_bf16 v[32:47], v[152:155], v[218:221], v[32:47]
	ds_read_b64_tr_b16 v[218:219], v169 offset:0x1600
	ds_read_b64_tr_b16 v[220:221], v169 offset:0x1e00
	v_mfma_f32_32x32x16_bf16 v[32:47], v[208:211], v[224:227], v[32:47]
	ds_read_b64_tr_b16 v[224:225], v169 offset:0x2600
	ds_read_b64_tr_b16 v[226:227], v169 offset:0x2e00
	v_mfma_f32_32x32x16_bf16 v[32:47], v[214:217], v[238:241], v[32:47]
	ds_read_b64_tr_b16 v[238:239], v169 offset:0x3600
	ds_read_b64_tr_b16 v[240:241], v169 offset:0x3e00
	s_waitcnt lgkmcnt(0)
	v_mfma_f32_32x32x16_bf16 v[16:31], v[148:151], v[160:163], v[16:31]
	v_max_f32_e32 v148, v81, v81
	v_max_f32_e32 v149, v80, v80
	v_max_f32_e32 v148, v149, v148
	v_max3_f32 v148, v148, v82, v83
	v_max3_f32 v148, v148, v84, v85
	v_max3_f32 v148, v148, v86, v87
	v_max3_f32 v148, v148, v88, v89
	v_max3_f32 v148, v148, v90, v91
	v_max3_f32 v148, v148, v92, v93
	v_mfma_f32_32x32x16_bf16 v[16:31], v[152:155], v[218:221], v[16:31]
	v_max3_f32 v148, v148, v94, v95
	v_max3_f32 v148, v148, v64, v65
	v_max3_f32 v148, v148, v66, v67
	v_max3_f32 v148, v148, v68, v69
	v_max3_f32 v148, v148, v70, v71
	v_max3_f32 v148, v148, v72, v73
	v_max3_f32 v148, v148, v74, v75
	v_max3_f32 v148, v148, v76, v77
	v_mfma_f32_32x32x16_bf16 v[16:31], v[208:211], v[224:227], v[16:31]
	v_max3_f32 v148, v148, v78, v79
	v_mov_b32_e32 v149, v148
	s_nop 1
	v_permlane32_swap_b32_e32 v148, v149
	v_max_f32_e32 v149, v149, v149
	v_max_f32_e32 v148, v148, v148
	v_max_f32_e32 v148, v148, v149
	v_sub_f32_e32 v149, v148, v197
	v_cmp_ge_f32_e32 vcc, s88, v149
	v_max_f32_e32 v149, v197, v197
	v_max_f32_e32 v149, v149, v148
	v_mfma_f32_32x32x16_bf16 v[16:31], v[214:217], v[238:241], v[16:31]
	v_sub_f32_e32 v148, v197, v149
	v_mul_f32_e32 v148, 0x3dd53b94, v148
	v_exp_f32_e32 v148, v148
	s_cmp_eq_u64 vcc, exec
	s_cselect_b64 s[8:9], -1, 0
	s_waitcnt vmcnt(0)
	v_cndmask_b32_e64 v148, v148, 1.0, s[8:9]
	v_cmp_gt_f32_e32 vcc, 1.0, v148
	ds_write_b128 v248, v[128:131]
	ds_write_b128 v249, v[132:135]
	ds_write_b128 v172, v[136:139] offset:49152
	ds_write_b128 v173, v[140:143] offset:49152
	ds_write_b128 v196, v[144:147]
	s_cbranch_vccz .Latt_u1_616
	s_and_saveexec_b64 s[10:11], s[6:7]
	ds_write_b32 v166, v148 offset:128
	s_or_b64 exec, exec, s[10:11]
	s_waitcnt lgkmcnt(0)
	v_add_u32_e32 v140, s1, v212
	ds_read_b128 v[128:131], v140 offset:224
	ds_read_b128 v[132:135], v140 offset:192
	ds_read_b128 v[136:139], v140 offset:160
	ds_read_b128 v[140:143], v140 offset:128
	s_waitcnt lgkmcnt(3)
	v_pk_mul_f32 v[12:13], v[12:13], v[128:129]
	s_waitcnt lgkmcnt(2)
	v_pk_mul_f32 v[8:9], v[8:9], v[132:133]
	s_waitcnt lgkmcnt(1)
	v_pk_mul_f32 v[4:5], v[4:5], v[136:137]
	v_pk_mul_f32 v[14:15], v[14:15], v[130:131]
	v_pk_mul_f32 v[10:11], v[10:11], v[134:135]
	v_pk_mul_f32 v[6:7], v[6:7], v[138:139]
	s_waitcnt lgkmcnt(0)
	v_pk_mul_f32 v[2:3], v[2:3], v[142:143]
	v_pk_mul_f32 v[0:1], v[0:1], v[140:141]
	v_pk_mul_f32 v[60:61], v[60:61], v[128:129]
	v_pk_mul_f32 v[56:57], v[56:57], v[132:133]
	v_pk_mul_f32 v[52:53], v[52:53], v[136:137]
	v_pk_mul_f32 v[62:63], v[62:63], v[130:131]
	v_pk_mul_f32 v[58:59], v[58:59], v[134:135]
	v_pk_mul_f32 v[54:55], v[54:55], v[138:139]
	v_pk_mul_f32 v[50:51], v[50:51], v[142:143]
	v_pk_mul_f32 v[48:49], v[48:49], v[140:141]
	v_pk_mul_f32 v[44:45], v[44:45], v[128:129]
	v_pk_mul_f32 v[40:41], v[40:41], v[132:133]
	v_pk_mul_f32 v[36:37], v[36:37], v[136:137]
	v_pk_mul_f32 v[46:47], v[46:47], v[130:131]
	v_pk_mul_f32 v[42:43], v[42:43], v[134:135]
	v_pk_mul_f32 v[38:39], v[38:39], v[138:139]
	v_pk_mul_f32 v[34:35], v[34:35], v[142:143]
	v_pk_mul_f32 v[32:33], v[32:33], v[140:141]
	v_pk_mul_f32 v[28:29], v[28:29], v[128:129]
	v_pk_mul_f32 v[24:25], v[24:25], v[132:133]
	v_pk_mul_f32 v[20:21], v[20:21], v[136:137]
	v_pk_mul_f32 v[30:31], v[30:31], v[130:131]
	v_pk_mul_f32 v[26:27], v[26:27], v[134:135]
	v_pk_mul_f32 v[22:23], v[22:23], v[138:139]
	v_pk_mul_f32 v[18:19], v[18:19], v[142:143]
	v_pk_mul_f32 v[16:17], v[16:17], v[140:141]
.Latt_u1_616:
	v_cndmask_b32_e64 v197, v149, v197, s[8:9]
	v_mul_f32_e32 v134, 0xbdd53b94, v197
	v_mov_b32_e32 v135, v134
	v_fmamk_f32 v80, v80, 0x3dd53b94, v134
	v_fmamk_f32 v81, v81, 0x3dd53b94, v134
	v_fmamk_f32 v82, v82, 0x3dd53b94, v134
	v_fmamk_f32 v83, v83, 0x3dd53b94, v134
	v_fmamk_f32 v84, v84, 0x3dd53b94, v134
	v_fmamk_f32 v85, v85, 0x3dd53b94, v134
	v_fmamk_f32 v86, v86, 0x3dd53b94, v134
	v_fmamk_f32 v87, v87, 0x3dd53b94, v134
	v_fmamk_f32 v88, v88, 0x3dd53b94, v134
	v_fmamk_f32 v89, v89, 0x3dd53b94, v134
	v_fmamk_f32 v90, v90, 0x3dd53b94, v134
	v_fmamk_f32 v91, v91, 0x3dd53b94, v134
	v_fmamk_f32 v92, v92, 0x3dd53b94, v134
	v_fmamk_f32 v93, v93, 0x3dd53b94, v134
	v_fmamk_f32 v94, v94, 0x3dd53b94, v134
	v_fmac_f32_e32 v135, 0x3dd53b94, v95
	v_exp_f32_e32 v162, v80
	v_exp_f32_e32 v205, v81
	v_exp_f32_e32 v149, v82
	v_exp_f32_e32 v163, v83
	v_exp_f32_e32 v150, v84
	v_exp_f32_e32 v161, v85
	v_exp_f32_e32 v151, v86
	v_exp_f32_e32 v160, v87
	v_exp_f32_e32 v152, v88
	v_exp_f32_e32 v155, v89
	v_exp_f32_e32 v153, v90
	v_exp_f32_e32 v154, v91
	v_exp_f32_e32 v145, v92
	v_exp_f32_e32 v147, v93
	v_exp_f32_e32 v144, v94
	v_exp_f32_e32 v146, v135
	v_pk_fma_f32 v[140:141], v[64:65], s[36:37], v[134:135] op_sel_hi:[1,0,0]
	v_add_f32_e32 v64, v202, v203
	v_fmac_f32_e32 v64, v194, v167
	v_add_f32_e32 v167, v206, v207
	s_add_i32 s3, s3, 2
	v_pk_fma_f32 v[138:139], v[66:67], s[36:37], v[134:135] op_sel_hi:[1,0,0]
	v_pk_fma_f32 v[132:133], v[68:69], s[36:37], v[134:135] op_sel_hi:[1,0,0]
	v_pk_fma_f32 v[130:131], v[70:71], s[36:37], v[134:135] op_sel_hi:[1,0,0]
	v_pk_fma_f32 v[128:129], v[72:73], s[36:37], v[134:135] op_sel_hi:[1,0,0]
	v_pk_fma_f32 v[142:143], v[74:75], s[36:37], v[134:135] op_sel_hi:[1,0,0]
	v_pk_fma_f32 v[136:137], v[76:77], s[36:37], v[134:135] op_sel_hi:[1,0,0]
	v_pk_fma_f32 v[134:135], v[78:79], s[36:37], v[134:135] op_sel_hi:[1,0,0]
	v_fmac_f32_e32 v167, v64, v204
	s_cmp_gt_u32 s3, 28
	s_waitcnt lgkmcnt(0)
	s_barrier
; __device__ __forceinline__ void finishSM(f32x16& p0, f32x16& p1, float alpha, float& l_reg, bf16x8& pa0, bf16x8& pa1, bf16x8& pa2, bf16x8& pa3) {
; #pragma unroll
;     for (int r = 0; r < 16; ++r) p1[r] = __builtin_amdgcn_exp2f(p1[r]);
;     float ps = 0;
; #pragma unroll
;     for (int r = 0; r < 16; ++r) ps += p0[r];
; #pragma unroll
;     for (int r = 0; r < 16; ++r) ps += p1[r];
;     { auto rr = __builtin_amdgcn_permlane32_swap(__float_as_uint(ps), __float_as_uint(ps), false, false);
;       ps = __uint_as_float(rr[0]) + __uint_as_float(rr[1]); }
;     l_reg = l_reg * alpha + ps;
; __device__ __forceinline__ void qkt(f32x16& p0, f32x16& p1, const char* Ks, const char* Rs, const bf16x8* qr, const char* Qp, int r32, int hi) {
;     p0 = f32x16{}; p1 = f32x16{};
; #pragma unroll
;     for (int d0 = 0; d0 < 8; ++d0) { const int cb = (d0 * 16 + hi * 8) * 2;
;         const bf16x8 b0 = *reinterpret_cast<const bf16x8*>(Ks + KSWZ(r32, cb));
;         const bf16x8 b1 = *reinterpret_cast<const bf16x8*>(Ks + KSWZ(32 + r32, cb));
;         p0 = __builtin_amdgcn_mfma_f32_32x32x16_bf16(b0, qr[d0], p0, 0, 0, 0);
;         p1 = __builtin_amdgcn_mfma_f32_32x32x16_bf16(b1, qr[d0], p1, 0, 0, 0); }
; #pragma unroll
;     for (int d0 = 0; d0 < 4; ++d0) { const int cb = (d0 * 16 + hi * 8) * 2;
;         const bf16x8 b0 = *reinterpret_cast<const bf16x8*>(Rs + RSWZ(r32, cb));
;         const bf16x8 b1 = *reinterpret_cast<const bf16x8*>(Rs + RSWZ(32 + r32, cb));
;         const bf16x8 qq = *reinterpret_cast<const bf16x8*>(Qp + RSWZ(r32, cb));
;         p0 = __builtin_amdgcn_mfma_f32_32x32x16_bf16(b0, qq, p0, 0, 0, 0);
;         p1 = __builtin_amdgcn_mfma_f32_32x32x16_bf16(b1, qq, p1, 0, 0, 0); }
; }
	s_cbranch_scc1 .LBB0_618
	v_mov_b32_e32 v194, v148
	ds_read_b128 v[64:67], v174 offset:49152
	ds_read_b128 v[68:71], v174 offset:57344
	ds_read_b128 v[198:201], v180 offset:49152
	ds_read_b128 v[206:209], v180 offset:57344
	s_add_i32 s8, 0, 0x12000
	v_add_f32_e32 v148, 0, v162
	s_waitcnt lgkmcnt(3)
	v_mfma_f32_32x32x16_bf16 v[80:95], v[64:67], v[120:123], 0
	v_add_f32_e32 v148, v205, v148
	v_add_f32_e32 v148, v149, v148
	v_add_f32_e32 v148, v163, v148
	v_add_f32_e32 v148, v150, v148
	v_add_f32_e32 v148, v161, v148
	v_add_f32_e32 v148, v151, v148
	v_add_f32_e32 v148, v160, v148
	s_waitcnt lgkmcnt(2)
	v_mfma_f32_32x32x16_bf16 v[64:79], v[68:71], v[120:123], 0
	v_add_f32_e32 v148, v152, v148
	v_add_f32_e32 v148, v155, v148
	v_add_f32_e32 v148, v153, v148
	v_add_f32_e32 v148, v154, v148
	v_exp_f32_e32 v140, v140
	v_add_f32_e32 v148, v145, v148
	v_exp_f32_e32 v141, v141
	s_waitcnt lgkmcnt(1)
	v_mfma_f32_32x32x16_bf16 v[80:95], v[198:201], v[124:127], v[80:95]
	v_add_f32_e32 v148, v147, v148
	v_exp_f32_e32 v138, v138
	v_add_f32_e32 v148, v144, v148
	v_exp_f32_e32 v139, v139
	v_add_f32_e32 v148, v146, v148
	v_exp_f32_e32 v132, v132
	v_add_f32_e32 v148, v140, v148
	s_waitcnt lgkmcnt(0)
	v_mfma_f32_32x32x16_bf16 v[64:79], v[206:209], v[124:127], v[64:79]
	ds_read_b128 v[198:201], v182 offset:49152
	ds_read_b128 v[206:209], v182 offset:57344
	v_exp_f32_e32 v133, v133
	v_add_f32_e32 v148, v141, v148
	v_exp_f32_e32 v130, v130
	v_add_f32_e32 v148, v138, v148
	v_exp_f32_e32 v131, v131
	v_add_f32_e32 v148, v139, v148
	s_waitcnt lgkmcnt(1)
	v_mfma_f32_32x32x16_bf16 v[80:95], v[198:201], v[116:119], v[80:95]
	v_exp_f32_e32 v128, v128
	v_add_f32_e32 v148, v132, v148
	v_exp_f32_e32 v129, v129
	v_add_f32_e32 v148, v133, v148
	v_exp_f32_e32 v142, v142
	v_add_f32_e32 v148, v130, v148
	v_exp_f32_e32 v143, v143
	s_waitcnt lgkmcnt(0)
	v_mfma_f32_32x32x16_bf16 v[64:79], v[206:209], v[116:119], v[64:79]
	ds_read_b128 v[198:201], v184 offset:49152
	ds_read_b128 v[206:209], v184 offset:57344
	v_add_f32_e32 v148, v131, v148
	v_exp_f32_e32 v136, v136
	v_add_f32_e32 v148, v128, v148
	v_exp_f32_e32 v137, v137
	v_add_f32_e32 v148, v129, v148
	v_exp_f32_e32 v134, v134
	s_waitcnt lgkmcnt(1)
	v_mfma_f32_32x32x16_bf16 v[80:95], v[198:201], v[112:115], v[80:95]
	v_add_f32_e32 v148, v142, v148
	v_exp_f32_e32 v135, v135
	v_add_f32_e32 v148, v143, v148
	v_add_f32_e32 v148, v136, v148
	v_add_f32_e32 v148, v137, v148
	v_add_f32_e32 v148, v134, v148
	s_waitcnt lgkmcnt(0)
	v_mfma_f32_32x32x16_bf16 v[64:79], v[206:209], v[112:115], v[64:79]
	ds_read_b128 v[198:201], v185 offset:49152
	ds_read_b128 v[206:209], v185 offset:57344
	s_waitcnt lgkmcnt(1)
	v_mfma_f32_32x32x16_bf16 v[80:95], v[198:201], v[108:111], v[80:95]
	s_waitcnt lgkmcnt(0)
	v_mfma_f32_32x32x16_bf16 v[64:79], v[206:209], v[108:111], v[64:79]
	ds_read_b128 v[198:201], v183 offset:49152
	ds_read_b128 v[206:209], v183 offset:57344
	s_waitcnt lgkmcnt(1)
	v_mfma_f32_32x32x16_bf16 v[80:95], v[198:201], v[104:107], v[80:95]
	s_waitcnt lgkmcnt(0)
	v_mfma_f32_32x32x16_bf16 v[64:79], v[206:209], v[104:107], v[64:79]
	ds_read_b128 v[198:201], v181 offset:49152
	ds_read_b128 v[206:209], v181 offset:57344
	s_waitcnt lgkmcnt(1)
	v_mfma_f32_32x32x16_bf16 v[80:95], v[198:201], v[100:103], v[80:95]
	s_waitcnt lgkmcnt(0)
	v_mfma_f32_32x32x16_bf16 v[64:79], v[206:209], v[100:103], v[64:79]
	ds_read_b128 v[198:201], v179 offset:49152
	ds_read_b128 v[206:209], v179 offset:57344
	s_waitcnt lgkmcnt(1)
	v_mfma_f32_32x32x16_bf16 v[80:95], v[198:201], v[96:99], v[80:95]
	v_add_u32_e32 v199, s8, v186
	v_add_u32_e32 v198, s8, v188
	s_waitcnt lgkmcnt(0)
	v_mfma_f32_32x32x16_bf16 v[64:79], v[206:209], v[96:99], v[64:79]
	ds_read_b128 v[200:203], v199
	ds_read_b128 v[206:209], v199 offset:4096
	ds_read_b128 v[214:217], v177
	s_waitcnt lgkmcnt(0)
	v_mfma_f32_32x32x16_bf16 v[80:95], v[200:203], v[214:217], v[80:95]
	v_mfma_f32_32x32x16_bf16 v[64:79], v[206:209], v[214:217], v[64:79]
	ds_read_b128 v[200:203], v198
	ds_read_b128 v[206:209], v198 offset:4096
	ds_read_b128 v[214:217], v175
	s_waitcnt lgkmcnt(0)
	v_mfma_f32_32x32x16_bf16 v[80:95], v[200:203], v[214:217], v[80:95]
	v_add_u32_e32 v200, s8, v190
	v_add_u32_e32 v201, s8, v192
	v_add_f32_e32 v202, v135, v148
	v_mov_b32_e32 v203, v202
	s_nop 1
	v_permlane32_swap_b32_e32 v202, v203
	v_mfma_f32_32x32x16_bf16 v[64:79], v[206:209], v[214:217], v[64:79]
	ds_read_b128 v[206:209], v200
	ds_read_b128 v[214:217], v200 offset:4096
	ds_read_b128 v[218:221], v178
	s_waitcnt lgkmcnt(0)
	v_mfma_f32_32x32x16_bf16 v[80:95], v[206:209], v[218:221], v[80:95]
	v_mfma_f32_32x32x16_bf16 v[64:79], v[214:217], v[218:221], v[64:79]
	ds_read_b128 v[206:209], v201
	ds_read_b128 v[214:217], v201 offset:4096
	ds_read_b128 v[218:221], v176
	v_cvt_pk_bf16_f32 v148, v162, v205
	v_cvt_pk_bf16_f32 v149, v149, v163
	v_cvt_pk_bf16_f32 v150, v150, v161
	v_cvt_pk_bf16_f32 v151, v151, v160
	v_cvt_pk_bf16_f32 v152, v152, v155
	v_cvt_pk_bf16_f32 v153, v153, v154
	s_waitcnt lgkmcnt(0)
; #define SBAR() __builtin_amdgcn_sched_barrier(0)
; #define SWRITE(b) do { *(bf16x8*)(V_lds + (b) * SHM_V + vst0) = vs0; *(bf16x8*)(V_lds + (b) * SHM_V + vst1) = vs1; const int kc = sc * 2; \
;     *(bf16x8*)(K_lds + (b) * SHM_K + KSWZ(sr, kc)) = ks0; *(bf16x8*)(K_lds + (b) * SHM_K + KSWZ(32 + sr, kc)) = ks1; \
;     *(bf16x8*)(R_lds + (b) * SHM_R + RSWZ(rr, rc * 2)) = rs0; } while (0)
; #define SWAIT() asm volatile("s_waitcnt vmcnt(0)" ::: "memory")
; template <int D0> __device__ __forceinline__ void pv_one(f32x16& od, int vb, bf16x8 pa0, bf16x8 pa1, bf16x8 pa2, bf16x8 pa3) {
;     const s16x4 l0 = tr_read<v_rd_off(D0, 0, 0)>(vb), h0 = tr_read<v_rd_off(D0, 0, 1)>(vb), l1 = tr_read<v_rd_off(D0, 1, 0)>(vb), h1 = tr_read<v_rd_off(D0, 1, 1)>(vb);
;     const s16x4 l2 = tr_read<v_rd_off(D0, 2, 0)>(vb), h2 = tr_read<v_rd_off(D0, 2, 1)>(vb), l3 = tr_read<v_rd_off(D0, 3, 0)>(vb), h3 = tr_read<v_rd_off(D0, 3, 1)>(vb);
;     asm volatile("s_waitcnt lgkmcnt(0)" ::: "memory"); SBAR();
;     ...
;     od = __builtin_amdgcn_mfma_f32_32x32x16_bf16(pa0, PK(l0, h0), od, 0, 0, 0);
;     od = __builtin_amdgcn_mfma_f32_32x32x16_bf16(pa1, PK(l1, h1), od, 0, 0, 0);
;     od = __builtin_amdgcn_mfma_f32_32x32x16_bf16(pa2, PK(l2, h2), od, 0, 0, 0);
;     od = __builtin_amdgcn_mfma_f32_32x32x16_bf16(pa3, PK(l3, h3), od, 0, 0, 0);
;     ...
; }
; __device__ __forceinline__ void pv_d0(f32x16* o, int vb, bf16x8 pa0, bf16x8 pa1, bf16x8 pa2, bf16x8 pa3) {
;     pv_one<0>(o[0], vb, pa0, pa1, pa2, pa3); pv_one<1>(o[1], vb, pa0, pa1, pa2, pa3); pv_one<2>(o[2], vb, pa0, pa1, pa2, pa3); pv_one<3>(o[3], vb, pa0, pa1, pa2, pa3);
; __device__ __forceinline__ void attn_body(const bf16_t* __restrict__ Qb, const bf16_t* __restrict__ Kh, const bf16_t* __restrict__ Vh, const bf16_t* __restrict__ Rh,
;                                           bf16_t* __restrict__ Zb, int seq, char* lds, int wv, bool nowrite) {
;     ...
;     for (int j = 1; j + 1 < NT; j += 2) {
;         SBAR(); qkt(pB0, pB1, K_lds + SHM_K, R_lds + SHM_R, qr, Qp, r32, hi);
;         finishSM(pA0, pA1, alA, l_reg, pa0, pa1, pa2, pa3); SBAR();
;         SLOAD((j + 1) * KVBLK); SBAR();
;         pv_d0(o, vb0, pa0, pa1, pa2, pa3); partialSM(pB0, pB1, m_reg, mnB, alB);
;         __syncthreads(); SWAIT(); SWRITE(0);
	v_mfma_f32_32x32x16_bf16 v[80:95], v[206:209], v[218:221], v[80:95]
	v_cvt_pk_bf16_f32 v154, v145, v147
	v_cvt_pk_bf16_f32 v155, v144, v146
	v_cvt_pk_bf16_f32 v204, v140, v141
	v_cvt_pk_bf16_f32 v205, v138, v139
	v_cvt_pk_bf16_f32 v206, v132, v133
	v_permlane32_swap_b32_e32 v148, v150
	v_mfma_f32_32x32x16_bf16 v[64:79], v[214:217], v[218:221], v[64:79]
	v_cvt_pk_bf16_f32 v207, v130, v131
	v_permlane32_swap_b32_e32 v204, v206
	v_cvt_pk_bf16_f32 v208, v128, v129
	v_cvt_pk_bf16_f32 v209, v142, v143
	v_cvt_pk_bf16_f32 v210, v136, v137
	v_cvt_pk_bf16_f32 v211, v134, v135
	v_permlane32_swap_b32_e32 v149, v151
	v_permlane32_swap_b32_e32 v152, v154
	v_permlane32_swap_b32_e32 v153, v155
	v_permlane32_swap_b32_e32 v205, v207
	v_permlane32_swap_b32_e32 v208, v210
	v_permlane32_swap_b32_e32 v209, v211
	global_load_dwordx4 v[128:131], v242, s[44:45]
	global_load_dwordx4 v[132:135], v243, s[44:45]
	global_load_dwordx4 v[136:139], v244, s[44:45]
	global_load_dwordx4 v[140:143], v245, s[44:45]
	global_load_dwordx4 v[144:147], v246, s[44:45]
	v_add_u32_e32 v242, 0x40000, v242
	v_add_u32_e32 v243, 0x40000, v243
	v_add_u32_e32 v244, 0x40000, v244
	v_add_u32_e32 v245, 0x40000, v245
	v_add_u32_e32 v246, 0x2000, v246
	ds_read_b64_tr_b16 v[214:215], v168 offset:0
	ds_read_b64_tr_b16 v[216:217], v168 offset:0x800
	ds_read_b64_tr_b16 v[218:219], v168 offset:0x1000
	ds_read_b64_tr_b16 v[220:221], v168 offset:0x1800
	ds_read_b64_tr_b16 v[224:225], v168 offset:0x2000
	ds_read_b64_tr_b16 v[226:227], v168 offset:0x2800
	ds_read_b64_tr_b16 v[238:239], v168 offset:0x3000
	ds_read_b64_tr_b16 v[240:241], v168 offset:0x3800
	s_waitcnt lgkmcnt(0)
	s_nop 0
	v_mfma_f32_32x32x16_bf16 v[0:15], v[148:151], v[214:217], v[0:15]
	ds_read_b64_tr_b16 v[214:215], v168 offset:0x200
	ds_read_b64_tr_b16 v[216:217], v168 offset:0xa00
	v_mfma_f32_32x32x16_bf16 v[0:15], v[152:155], v[218:221], v[0:15]
	ds_read_b64_tr_b16 v[218:219], v168 offset:0x1200
	ds_read_b64_tr_b16 v[220:221], v168 offset:0x1a00
	v_mfma_f32_32x32x16_bf16 v[0:15], v[204:207], v[224:227], v[0:15]
	ds_read_b64_tr_b16 v[224:225], v168 offset:0x2200
	ds_read_b64_tr_b16 v[226:227], v168 offset:0x2a00
	v_mfma_f32_32x32x16_bf16 v[0:15], v[208:211], v[238:241], v[0:15]
	ds_read_b64_tr_b16 v[238:239], v168 offset:0x3200
	ds_read_b64_tr_b16 v[240:241], v168 offset:0x3a00
	s_waitcnt lgkmcnt(0)
	v_mfma_f32_32x32x16_bf16 v[48:63], v[148:151], v[214:217], v[48:63]
	ds_read_b64_tr_b16 v[214:215], v168 offset:0x400
	ds_read_b64_tr_b16 v[216:217], v168 offset:0xc00
	v_mfma_f32_32x32x16_bf16 v[48:63], v[152:155], v[218:221], v[48:63]
	ds_read_b64_tr_b16 v[218:219], v168 offset:0x1400
	ds_read_b64_tr_b16 v[220:221], v168 offset:0x1c00
	v_mfma_f32_32x32x16_bf16 v[48:63], v[204:207], v[224:227], v[48:63]
	ds_read_b64_tr_b16 v[224:225], v168 offset:0x2400
	ds_read_b64_tr_b16 v[226:227], v168 offset:0x2c00
	v_mfma_f32_32x32x16_bf16 v[48:63], v[208:211], v[238:241], v[48:63]
	ds_read_b64_tr_b16 v[238:239], v168 offset:0x3400
	ds_read_b64_tr_b16 v[240:241], v168 offset:0x3c00
	s_waitcnt lgkmcnt(0)
	v_mfma_f32_32x32x16_bf16 v[32:47], v[148:151], v[214:217], v[32:47]
	ds_read_b64_tr_b16 v[214:215], v168 offset:0x600
	ds_read_b64_tr_b16 v[216:217], v168 offset:0xe00
	v_mfma_f32_32x32x16_bf16 v[32:47], v[152:155], v[218:221], v[32:47]
	ds_read_b64_tr_b16 v[218:219], v168 offset:0x1600
	ds_read_b64_tr_b16 v[220:221], v168 offset:0x1e00
	v_mfma_f32_32x32x16_bf16 v[32:47], v[204:207], v[224:227], v[32:47]
	ds_read_b64_tr_b16 v[224:225], v168 offset:0x2600
	ds_read_b64_tr_b16 v[226:227], v168 offset:0x2e00
	v_mfma_f32_32x32x16_bf16 v[32:47], v[208:211], v[238:241], v[32:47]
	ds_read_b64_tr_b16 v[238:239], v168 offset:0x3600
	ds_read_b64_tr_b16 v[240:241], v168 offset:0x3e00
	s_waitcnt lgkmcnt(0)
	v_mfma_f32_32x32x16_bf16 v[16:31], v[148:151], v[214:217], v[16:31]
	v_max_f32_e32 v148, v81, v81
	v_max_f32_e32 v149, v80, v80
	v_max_f32_e32 v148, v149, v148
	v_max3_f32 v148, v148, v82, v83
	v_max3_f32 v148, v148, v84, v85
	v_max3_f32 v148, v148, v86, v87
	v_max3_f32 v148, v148, v88, v89
	v_max3_f32 v148, v148, v90, v91
	v_max3_f32 v148, v148, v92, v93
	v_mfma_f32_32x32x16_bf16 v[16:31], v[152:155], v[218:221], v[16:31]
	v_max3_f32 v148, v148, v94, v95
	v_max3_f32 v148, v148, v64, v65
	v_max3_f32 v148, v148, v66, v67
	v_max3_f32 v148, v148, v68, v69
	v_max3_f32 v148, v148, v70, v71
	v_max3_f32 v148, v148, v72, v73
	v_max3_f32 v148, v148, v74, v75
	v_max3_f32 v148, v148, v76, v77
	v_mfma_f32_32x32x16_bf16 v[16:31], v[204:207], v[224:227], v[16:31]
	v_max3_f32 v148, v148, v78, v79
	v_mov_b32_e32 v149, v148
	s_nop 1
	v_permlane32_swap_b32_e32 v148, v149
	v_max_f32_e32 v149, v149, v149
	v_max_f32_e32 v148, v148, v148
	v_max_f32_e32 v148, v148, v149
	v_sub_f32_e32 v149, v148, v197
	v_cmp_ge_f32_e32 vcc, s88, v149
	v_max_f32_e32 v149, v197, v197
	v_max_f32_e32 v148, v149, v148
	v_mfma_f32_32x32x16_bf16 v[16:31], v[208:211], v[238:241], v[16:31]
	v_sub_f32_e32 v149, v197, v148
	v_mul_f32_e32 v149, 0x3dd53b94, v149
	v_exp_f32_e32 v149, v149
	s_cmp_eq_u64 vcc, exec
	s_cselect_b64 s[8:9], -1, 0
	s_waitcnt vmcnt(0)
	v_cndmask_b32_e64 v204, v149, 1.0, s[8:9]
	ds_write_b128 v170, v[128:131]
	ds_write_b128 v171, v[132:135]
	ds_write_b128 v172, v[136:139] offset:32768
	ds_write_b128 v173, v[140:143] offset:32768
	v_add_u32_e32 v128, 0x10000, v195
	v_cmp_gt_f32_e32 vcc, 1.0, v204
	ds_write_b128 v128, v[144:147]
	s_cbranch_vccz .Latt_u2_612
; __device__ __forceinline__ void partialSM(f32x16& p0, f32x16& p1, float& m_reg, float& mn, float& alpha) {
;     ...
;     if (__builtin_expect(__all(pmax - m_reg <= THR / SCALE), 1)) { mn = m_reg; alpha = 1.f; }
;     else { mn = fmaxf(m_reg, pmax); alpha = __builtin_amdgcn_exp2f((m_reg - mn) * C); m_reg = mn; }
;     const float mnC = -mn * C;
; #pragma unroll
;     for (int r = 0; r < 16; ++r) p0[r] = fmaf(p0[r], C, mnC);
; #pragma unroll
;     for (int r = 0; r < 16; ++r) p1[r] = fmaf(p1[r], C, mnC);
; #pragma unroll
;     for (int r = 0; r < 16; ++r) p0[r] = __builtin_amdgcn_exp2f(p0[r]);
	s_and_saveexec_b64 s[10:11], s[6:7]
	ds_write_b32 v166, v204 offset:128
	s_or_b64 exec, exec, s[10:11]
	s_waitcnt lgkmcnt(0)
	v_add_u32_e32 v140, s1, v212
	ds_read_b128 v[128:131], v140 offset:224
	ds_read_b128 v[132:135], v140 offset:192
	ds_read_b128 v[136:139], v140 offset:160
	ds_read_b128 v[140:143], v140 offset:128
	s_waitcnt lgkmcnt(3)
	v_pk_mul_f32 v[12:13], v[12:13], v[128:129]
	s_waitcnt lgkmcnt(2)
	v_pk_mul_f32 v[8:9], v[8:9], v[132:133]
	s_waitcnt lgkmcnt(1)
	v_pk_mul_f32 v[4:5], v[4:5], v[136:137]
	v_pk_mul_f32 v[14:15], v[14:15], v[130:131]
	v_pk_mul_f32 v[10:11], v[10:11], v[134:135]
	v_pk_mul_f32 v[6:7], v[6:7], v[138:139]
	s_waitcnt lgkmcnt(0)
	v_pk_mul_f32 v[2:3], v[2:3], v[142:143]
	v_pk_mul_f32 v[0:1], v[0:1], v[140:141]
	v_pk_mul_f32 v[60:61], v[60:61], v[128:129]
	v_pk_mul_f32 v[56:57], v[56:57], v[132:133]
	v_pk_mul_f32 v[52:53], v[52:53], v[136:137]
	v_pk_mul_f32 v[62:63], v[62:63], v[130:131]
	v_pk_mul_f32 v[58:59], v[58:59], v[134:135]
	v_pk_mul_f32 v[54:55], v[54:55], v[138:139]
	v_pk_mul_f32 v[50:51], v[50:51], v[142:143]
	v_pk_mul_f32 v[48:49], v[48:49], v[140:141]
	v_pk_mul_f32 v[44:45], v[44:45], v[128:129]
	v_pk_mul_f32 v[40:41], v[40:41], v[132:133]
	v_pk_mul_f32 v[36:37], v[36:37], v[136:137]
	v_pk_mul_f32 v[46:47], v[46:47], v[130:131]
	v_pk_mul_f32 v[42:43], v[42:43], v[134:135]
	v_pk_mul_f32 v[38:39], v[38:39], v[138:139]
	v_pk_mul_f32 v[34:35], v[34:35], v[142:143]
	v_pk_mul_f32 v[32:33], v[32:33], v[140:141]
	v_pk_mul_f32 v[28:29], v[28:29], v[128:129]
	v_pk_mul_f32 v[24:25], v[24:25], v[132:133]
	v_pk_mul_f32 v[20:21], v[20:21], v[136:137]
	v_pk_mul_f32 v[30:31], v[30:31], v[130:131]
	v_pk_mul_f32 v[26:27], v[26:27], v[134:135]
	v_pk_mul_f32 v[22:23], v[22:23], v[138:139]
	v_pk_mul_f32 v[18:19], v[18:19], v[142:143]
	v_pk_mul_f32 v[16:17], v[16:17], v[140:141]
.Latt_u2_612:
	v_cndmask_b32_e64 v197, v148, v197, s[8:9]
	v_mul_f32_e32 v144, 0xbdd53b94, v197
	v_fmamk_f32 v80, v80, 0x3dd53b94, v144
	v_fmamk_f32 v81, v81, 0x3dd53b94, v144
	v_fmamk_f32 v82, v82, 0x3dd53b94, v144
	v_fmamk_f32 v83, v83, 0x3dd53b94, v144
	v_fmamk_f32 v84, v84, 0x3dd53b94, v144
	v_fmamk_f32 v85, v85, 0x3dd53b94, v144
	v_fmamk_f32 v86, v86, 0x3dd53b94, v144
	v_fmamk_f32 v87, v87, 0x3dd53b94, v144
	v_fmamk_f32 v88, v88, 0x3dd53b94, v144
	v_fmamk_f32 v89, v89, 0x3dd53b94, v144
	v_fmamk_f32 v90, v90, 0x3dd53b94, v144
	v_fmamk_f32 v91, v91, 0x3dd53b94, v144
	v_fmamk_f32 v92, v92, 0x3dd53b94, v144
	v_fmamk_f32 v93, v93, 0x3dd53b94, v144
	v_fmamk_f32 v94, v94, 0x3dd53b94, v144
	v_fmamk_f32 v95, v95, 0x3dd53b94, v144
	v_fmamk_f32 v206, v68, 0x3dd53b94, v144
	v_fmamk_f32 v148, v71, 0x3dd53b94, v144
	v_fmamk_f32 v149, v72, 0x3dd53b94, v144
	v_fmamk_f32 v207, v77, 0x3dd53b94, v144
	v_fmamk_f32 v153, v64, 0x3dd53b94, v144
	v_fmamk_f32 v154, v65, 0x3dd53b94, v144
	v_fmamk_f32 v155, v66, 0x3dd53b94, v144
	v_fmamk_f32 v205, v67, 0x3dd53b94, v144
	v_fmamk_f32 v146, v69, 0x3dd53b94, v144
	v_fmamk_f32 v147, v70, 0x3dd53b94, v144
	v_fmamk_f32 v150, v73, 0x3dd53b94, v144
	v_fmamk_f32 v151, v74, 0x3dd53b94, v144
	v_fmamk_f32 v152, v75, 0x3dd53b94, v144
	v_fmamk_f32 v145, v76, 0x3dd53b94, v144
	v_exp_f32_e32 v141, v80
	v_exp_f32_e32 v143, v81
	v_exp_f32_e32 v139, v82
	v_exp_f32_e32 v142, v83
	v_exp_f32_e32 v138, v84
	v_exp_f32_e32 v140, v85
	v_exp_f32_e32 v136, v86
	v_exp_f32_e32 v137, v87
	v_exp_f32_e32 v133, v88
	v_exp_f32_e32 v135, v89
	v_exp_f32_e32 v132, v90
	v_exp_f32_e32 v134, v91
	v_exp_f32_e32 v129, v92
	v_exp_f32_e32 v131, v93
	v_exp_f32_e32 v128, v94
	v_exp_f32_e32 v130, v95
	v_fmamk_f32 v208, v78, 0x3dd53b94, v144
	v_fmac_f32_e32 v144, 0x3dd53b94, v79
	s_waitcnt lgkmcnt(0)
	s_barrier
	ds_read_b128 v[64:67], v174 offset:32768
	ds_read_b128 v[68:71], v174 offset:40960
	ds_read_b128 v[214:217], v180 offset:32768
	ds_read_b128 v[218:221], v180 offset:40960
	v_exp_f32_e32 v209, v153
	v_exp_f32_e32 v210, v154
	s_waitcnt lgkmcnt(3)
	v_mfma_f32_32x32x16_bf16 v[80:95], v[64:67], v[120:123], 0
	v_exp_f32_e32 v211, v155
	v_exp_f32_e32 v205, v205
	v_exp_f32_e32 v146, v146
	v_exp_f32_e32 v147, v147
	v_exp_f32_e32 v145, v145
	v_exp_f32_e32 v144, v144
	s_waitcnt lgkmcnt(2)
	v_mfma_f32_32x32x16_bf16 v[64:79], v[68:71], v[120:123], 0
	s_waitcnt lgkmcnt(1)
	v_mfma_f32_32x32x16_bf16 v[80:95], v[214:217], v[124:127], v[80:95]
	s_waitcnt lgkmcnt(0)
	v_mfma_f32_32x32x16_bf16 v[64:79], v[218:221], v[124:127], v[64:79]
	ds_read_b128 v[214:217], v182 offset:32768
	ds_read_b128 v[218:221], v182 offset:40960
	s_waitcnt lgkmcnt(1)
	v_mfma_f32_32x32x16_bf16 v[80:95], v[214:217], v[116:119], v[80:95]
	s_waitcnt lgkmcnt(0)
	v_mfma_f32_32x32x16_bf16 v[64:79], v[218:221], v[116:119], v[64:79]
	ds_read_b128 v[214:217], v184 offset:32768
	ds_read_b128 v[218:221], v184 offset:40960
	s_waitcnt lgkmcnt(1)
	v_mfma_f32_32x32x16_bf16 v[80:95], v[214:217], v[112:115], v[80:95]
	s_waitcnt lgkmcnt(0)
	v_mfma_f32_32x32x16_bf16 v[64:79], v[218:221], v[112:115], v[64:79]
	ds_read_b128 v[214:217], v185 offset:32768
	ds_read_b128 v[218:221], v185 offset:40960
	s_waitcnt lgkmcnt(1)
	v_mfma_f32_32x32x16_bf16 v[80:95], v[214:217], v[108:111], v[80:95]
	s_waitcnt lgkmcnt(0)
	v_mfma_f32_32x32x16_bf16 v[64:79], v[218:221], v[108:111], v[64:79]
	ds_read_b128 v[214:217], v183 offset:32768
	ds_read_b128 v[218:221], v183 offset:40960
	s_waitcnt lgkmcnt(1)
	v_mfma_f32_32x32x16_bf16 v[80:95], v[214:217], v[104:107], v[80:95]
	s_waitcnt lgkmcnt(0)
	v_mfma_f32_32x32x16_bf16 v[64:79], v[218:221], v[104:107], v[64:79]
	ds_read_b128 v[214:217], v181 offset:32768
	ds_read_b128 v[218:221], v181 offset:40960
	s_waitcnt lgkmcnt(1)
	v_mfma_f32_32x32x16_bf16 v[80:95], v[214:217], v[100:103], v[80:95]
	s_waitcnt lgkmcnt(0)
; #define SBAR() __builtin_amdgcn_sched_barrier(0)
; __device__ __forceinline__ void finishSM(f32x16& p0, f32x16& p1, float alpha, float& l_reg, bf16x8& pa0, bf16x8& pa1, bf16x8& pa2, bf16x8& pa3) {
; #pragma unroll
;     for (int r = 0; r < 16; ++r) p1[r] = __builtin_amdgcn_exp2f(p1[r]);
;     float ps = 0;
; #pragma unroll
;     for (int r = 0; r < 16; ++r) ps += p0[r];
; #pragma unroll
;     for (int r = 0; r < 16; ++r) ps += p1[r];
;     { auto rr = __builtin_amdgcn_permlane32_swap(__float_as_uint(ps), __float_as_uint(ps), false, false);
;       ps = __uint_as_float(rr[0]) + __uint_as_float(rr[1]); }
;     l_reg = l_reg * alpha + ps;
;     ...
;     PK4(p0, 0, pa0); PK4(p0, 8, pa1); PK4(p1, 0, pa2); PK4(p1, 8, pa3);
; __device__ __forceinline__ void attn_body(const bf16_t* __restrict__ Qb, const bf16_t* __restrict__ Kh, const bf16_t* __restrict__ Vh, const bf16_t* __restrict__ Rh,
;                                           bf16_t* __restrict__ Zb, int seq, char* lds, int wv, bool nowrite) {
;     ...
;         SBAR(); qkt(pA0, pA1, K_lds, R_lds, qr, Qp, r32, hi);
;         finishSM(pB0, pB1, alB, l_reg, pa0, pa1, pa2, pa3); SBAR();
;         SLOAD((j + 2) * KVBLK); SBAR();
;         pv_d0(o, vb0 + SHM_V, pa0, pa1, pa2, pa3); partialSM(pA0, pA1, m_reg, mnA, alA);
	v_mfma_f32_32x32x16_bf16 v[64:79], v[218:221], v[100:103], v[64:79]
	ds_read_b128 v[214:217], v179 offset:32768
	ds_read_b128 v[218:221], v179 offset:40960
	s_waitcnt lgkmcnt(1)
	v_mfma_f32_32x32x16_bf16 v[80:95], v[214:217], v[96:99], v[80:95]
	s_waitcnt lgkmcnt(0)
	v_mfma_f32_32x32x16_bf16 v[64:79], v[218:221], v[96:99], v[64:79]
	ds_read_b128 v[214:217], v187
	ds_read_b128 v[218:221], v187 offset:4096
	ds_read_b128 v[224:227], v177
	s_waitcnt lgkmcnt(0)
	v_mfma_f32_32x32x16_bf16 v[80:95], v[214:217], v[224:227], v[80:95]
	v_mfma_f32_32x32x16_bf16 v[64:79], v[218:221], v[224:227], v[64:79]
	ds_read_b128 v[214:217], v189
	ds_read_b128 v[218:221], v189 offset:4096
	ds_read_b128 v[224:227], v175
	s_waitcnt lgkmcnt(0)
	v_mfma_f32_32x32x16_bf16 v[80:95], v[214:217], v[224:227], v[80:95]
	v_mfma_f32_32x32x16_bf16 v[64:79], v[218:221], v[224:227], v[64:79]
	ds_read_b128 v[214:217], v191
	ds_read_b128 v[218:221], v191 offset:4096
	ds_read_b128 v[224:227], v178
	s_waitcnt lgkmcnt(0)
	v_mfma_f32_32x32x16_bf16 v[80:95], v[214:217], v[224:227], v[80:95]
	v_mfma_f32_32x32x16_bf16 v[64:79], v[218:221], v[224:227], v[64:79]
	ds_read_b128 v[214:217], v193
	ds_read_b128 v[218:221], v193 offset:4096
	ds_read_b128 v[224:227], v176
	s_waitcnt lgkmcnt(0)
	v_mfma_f32_32x32x16_bf16 v[80:95], v[214:217], v[224:227], v[80:95]
	v_exp_f32_e32 v215, v148
	v_add_f32_e32 v148, 0, v141
	v_add_f32_e32 v148, v143, v148
	v_add_f32_e32 v148, v139, v148
	v_add_f32_e32 v148, v142, v148
	v_add_f32_e32 v148, v138, v148
	v_add_f32_e32 v148, v140, v148
	v_add_f32_e32 v148, v136, v148
	v_add_f32_e32 v148, v137, v148
	v_add_f32_e32 v148, v133, v148
	v_add_f32_e32 v148, v135, v148
	v_add_f32_e32 v148, v132, v148
	v_add_f32_e32 v148, v134, v148
	v_add_f32_e32 v148, v129, v148
	v_add_f32_e32 v148, v131, v148
	v_add_f32_e32 v148, v128, v148
	v_add_f32_e32 v148, v130, v148
	v_exp_f32_e32 v214, v206
	v_add_f32_e32 v148, v209, v148
	v_add_f32_e32 v148, v210, v148
	v_add_f32_e32 v148, v211, v148
	v_add_f32_e32 v148, v205, v148
	v_exp_f32_e32 v216, v149
	v_add_f32_e32 v148, v214, v148
	v_exp_f32_e32 v217, v150
	v_add_f32_e32 v148, v146, v148
	v_mfma_f32_32x32x16_bf16 v[64:79], v[218:221], v[224:227], v[64:79]
	v_exp_f32_e32 v218, v151
	v_add_f32_e32 v148, v147, v148
	v_exp_f32_e32 v219, v152
	v_add_f32_e32 v148, v215, v148
	v_add_f32_e32 v148, v216, v148
	v_exp_f32_e32 v220, v207
	v_add_f32_e32 v148, v217, v148
	v_exp_f32_e32 v221, v208
	v_add_f32_e32 v148, v218, v148
	v_add_f32_e32 v148, v219, v148
	v_add_f32_e32 v148, v145, v148
	v_add_f32_e32 v148, v220, v148
	v_add_f32_e32 v148, v221, v148
	v_add_f32_e32 v206, v144, v148
	v_mov_b32_e32 v207, v206
	v_cvt_pk_bf16_f32 v148, v141, v143
	v_cvt_pk_bf16_f32 v149, v139, v142
	v_cvt_pk_bf16_f32 v150, v138, v140
	v_cvt_pk_bf16_f32 v151, v136, v137
	s_nop 1
	v_permlane32_swap_b32_e32 v206, v207
	v_permlane32_swap_b32_e32 v148, v150
	v_permlane32_swap_b32_e32 v149, v151
	v_cvt_pk_bf16_f32 v152, v133, v135
	v_cvt_pk_bf16_f32 v153, v132, v134
	v_cvt_pk_bf16_f32 v154, v129, v131
	v_cvt_pk_bf16_f32 v155, v128, v130
	v_cvt_pk_bf16_f32 v208, v209, v210
	v_cvt_pk_bf16_f32 v209, v211, v205
	v_cvt_pk_bf16_f32 v210, v214, v146
	v_cvt_pk_bf16_f32 v211, v147, v215
	v_cvt_pk_bf16_f32 v214, v216, v217
	v_cvt_pk_bf16_f32 v215, v218, v219
	v_cvt_pk_bf16_f32 v216, v145, v220
	v_cvt_pk_bf16_f32 v217, v221, v144
	s_nop 0
	v_permlane32_swap_b32_e32 v152, v154
	v_permlane32_swap_b32_e32 v153, v155
	v_permlane32_swap_b32_e32 v208, v210
	v_permlane32_swap_b32_e32 v209, v211
	v_permlane32_swap_b32_e32 v214, v216
	v_permlane32_swap_b32_e32 v215, v217
	global_load_dwordx4 v[128:131], v242, s[44:45]
	global_load_dwordx4 v[132:135], v243, s[44:45]
	global_load_dwordx4 v[136:139], v244, s[44:45]
	global_load_dwordx4 v[140:143], v245, s[44:45]
	global_load_dwordx4 v[144:147], v246, s[44:45]
	v_add_u32_e32 v242, 0x40000, v242
	v_add_u32_e32 v243, 0x40000, v243
	v_add_u32_e32 v244, 0x40000, v244
	v_add_u32_e32 v245, 0x40000, v245
	v_add_u32_e32 v246, 0x2000, v246
	ds_read_b64_tr_b16 v[160:161], v247 offset:0
	ds_read_b64_tr_b16 v[162:163], v247 offset:0x800
	ds_read_b64_tr_b16 v[218:219], v247 offset:0x1000
	ds_read_b64_tr_b16 v[220:221], v247 offset:0x1800
	ds_read_b64_tr_b16 v[224:225], v247 offset:0x2000
	ds_read_b64_tr_b16 v[226:227], v247 offset:0x2800
	ds_read_b64_tr_b16 v[238:239], v247 offset:0x3000
	ds_read_b64_tr_b16 v[240:241], v247 offset:0x3800
	s_waitcnt lgkmcnt(0)
	s_nop 0
	v_mfma_f32_32x32x16_bf16 v[0:15], v[148:151], v[160:163], v[0:15]
	ds_read_b64_tr_b16 v[160:161], v247 offset:0x200
	ds_read_b64_tr_b16 v[162:163], v247 offset:0xa00
	v_mfma_f32_32x32x16_bf16 v[0:15], v[152:155], v[218:221], v[0:15]
	ds_read_b64_tr_b16 v[218:219], v247 offset:0x1200
	ds_read_b64_tr_b16 v[220:221], v247 offset:0x1a00
	v_mfma_f32_32x32x16_bf16 v[0:15], v[208:211], v[224:227], v[0:15]
	ds_read_b64_tr_b16 v[224:225], v247 offset:0x2200
	ds_read_b64_tr_b16 v[226:227], v247 offset:0x2a00
	v_mfma_f32_32x32x16_bf16 v[0:15], v[214:217], v[238:241], v[0:15]
	ds_read_b64_tr_b16 v[238:239], v247 offset:0x3200
	ds_read_b64_tr_b16 v[240:241], v247 offset:0x3a00
	s_waitcnt lgkmcnt(0)
; __device__ __forceinline__ void partialSM(f32x16& p0, f32x16& p1, float& m_reg, float& mn, float& alpha) {
;     constexpr float C = SCALE * 1.4426950408889634f;
;     float pmax = p0[0];
; #pragma unroll
;     for (int r = 1; r < 16; ++r) pmax = fmaxf(pmax, p0[r]);
; #pragma unroll
;     for (int r = 0; r < 16; ++r) pmax = fmaxf(pmax, p1[r]);
;     { auto rr = __builtin_amdgcn_permlane32_swap(__float_as_uint(pmax), __float_as_uint(pmax), false, false);
;       pmax = fmaxf(__uint_as_float(rr[0]), __uint_as_float(rr[1])); }
;     if (__builtin_expect(__all(pmax - m_reg <= THR / SCALE), 1)) { mn = m_reg; alpha = 1.f; }
;     else { mn = fmaxf(m_reg, pmax); alpha = __builtin_amdgcn_exp2f((m_reg - mn) * C); m_reg = mn; }
	v_mfma_f32_32x32x16_bf16 v[48:63], v[148:151], v[160:163], v[48:63]
	ds_read_b64_tr_b16 v[160:161], v247 offset:0x400
	ds_read_b64_tr_b16 v[162:163], v247 offset:0xc00
	v_mfma_f32_32x32x16_bf16 v[48:63], v[152:155], v[218:221], v[48:63]
	ds_read_b64_tr_b16 v[218:219], v247 offset:0x1400
	ds_read_b64_tr_b16 v[220:221], v247 offset:0x1c00
	v_mfma_f32_32x32x16_bf16 v[48:63], v[208:211], v[224:227], v[48:63]
	ds_read_b64_tr_b16 v[224:225], v247 offset:0x2400
	ds_read_b64_tr_b16 v[226:227], v247 offset:0x2c00
	v_mfma_f32_32x32x16_bf16 v[48:63], v[214:217], v[238:241], v[48:63]
	ds_read_b64_tr_b16 v[238:239], v247 offset:0x3400
	ds_read_b64_tr_b16 v[240:241], v247 offset:0x3c00
	s_waitcnt lgkmcnt(0)
	v_mfma_f32_32x32x16_bf16 v[32:47], v[148:151], v[160:163], v[32:47]
	ds_read_b64_tr_b16 v[160:161], v247 offset:0x600
	ds_read_b64_tr_b16 v[162:163], v247 offset:0xe00
	v_mfma_f32_32x32x16_bf16 v[32:47], v[152:155], v[218:221], v[32:47]
	ds_read_b64_tr_b16 v[218:219], v247 offset:0x1600
	ds_read_b64_tr_b16 v[220:221], v247 offset:0x1e00
	v_mfma_f32_32x32x16_bf16 v[32:47], v[208:211], v[224:227], v[32:47]
	ds_read_b64_tr_b16 v[224:225], v247 offset:0x2600
	ds_read_b64_tr_b16 v[226:227], v247 offset:0x2e00
	v_mfma_f32_32x32x16_bf16 v[32:47], v[214:217], v[238:241], v[32:47]
	ds_read_b64_tr_b16 v[238:239], v247 offset:0x3600
	ds_read_b64_tr_b16 v[240:241], v247 offset:0x3e00
	s_waitcnt lgkmcnt(0)
	v_mfma_f32_32x32x16_bf16 v[16:31], v[148:151], v[160:163], v[16:31]
	v_max_f32_e32 v148, v81, v81
	v_max_f32_e32 v149, v80, v80
	v_max_f32_e32 v148, v149, v148
	v_max3_f32 v148, v148, v82, v83
	v_max3_f32 v148, v148, v84, v85
	v_max3_f32 v148, v148, v86, v87
	v_max3_f32 v148, v148, v88, v89
	v_max3_f32 v148, v148, v90, v91
	v_max3_f32 v148, v148, v92, v93
	v_mfma_f32_32x32x16_bf16 v[16:31], v[152:155], v[218:221], v[16:31]
	v_max3_f32 v148, v148, v94, v95
	v_max3_f32 v148, v148, v64, v65
	v_max3_f32 v148, v148, v66, v67
	v_max3_f32 v148, v148, v68, v69
	v_max3_f32 v148, v148, v70, v71
	v_max3_f32 v148, v148, v72, v73
	v_max3_f32 v148, v148, v74, v75
	v_max3_f32 v148, v148, v76, v77
	v_mfma_f32_32x32x16_bf16 v[16:31], v[208:211], v[224:227], v[16:31]
	v_max3_f32 v148, v148, v78, v79
	v_mov_b32_e32 v149, v148
	s_nop 1
	v_permlane32_swap_b32_e32 v148, v149
	v_max_f32_e32 v149, v149, v149
	v_max_f32_e32 v148, v148, v148
	v_max_f32_e32 v148, v148, v149
	v_sub_f32_e32 v149, v148, v197
	v_cmp_ge_f32_e32 vcc, s88, v149
	v_max_f32_e32 v149, v197, v197
	v_max_f32_e32 v149, v149, v148
	v_mfma_f32_32x32x16_bf16 v[16:31], v[214:217], v[238:241], v[16:31]
	v_sub_f32_e32 v148, v197, v149
	v_mul_f32_e32 v148, 0x3dd53b94, v148
	v_exp_f32_e32 v148, v148
	s_cmp_eq_u64 vcc, exec
	s_cselect_b64 s[8:9], -1, 0
	s_waitcnt vmcnt(0)
	v_cndmask_b32_e64 v148, v148, 1.0, s[8:9]
	v_cmp_gt_f32_e32 vcc, 1.0, v148
	ds_write_b128 v170, v[128:131] offset:16384
	ds_write_b128 v171, v[132:135] offset:16384
	ds_write_b128 v172, v[136:139] offset:49152
	ds_write_b128 v173, v[140:143] offset:49152
	ds_write_b128 v196, v[144:147]
	s_cbranch_vccz .Latt_u2_616
	s_and_saveexec_b64 s[10:11], s[6:7]
	ds_write_b32 v166, v148 offset:128
	s_or_b64 exec, exec, s[10:11]
	s_waitcnt lgkmcnt(0)
	v_add_u32_e32 v140, s1, v212
	ds_read_b128 v[128:131], v140 offset:224
	ds_read_b128 v[132:135], v140 offset:192
	ds_read_b128 v[136:139], v140 offset:160
	ds_read_b128 v[140:143], v140 offset:128
	s_waitcnt lgkmcnt(3)
	v_pk_mul_f32 v[12:13], v[12:13], v[128:129]
	s_waitcnt lgkmcnt(2)
	v_pk_mul_f32 v[8:9], v[8:9], v[132:133]
	s_waitcnt lgkmcnt(1)
	v_pk_mul_f32 v[4:5], v[4:5], v[136:137]
	v_pk_mul_f32 v[14:15], v[14:15], v[130:131]
	v_pk_mul_f32 v[10:11], v[10:11], v[134:135]
	v_pk_mul_f32 v[6:7], v[6:7], v[138:139]
	s_waitcnt lgkmcnt(0)
	v_pk_mul_f32 v[2:3], v[2:3], v[142:143]
	v_pk_mul_f32 v[0:1], v[0:1], v[140:141]
	v_pk_mul_f32 v[60:61], v[60:61], v[128:129]
	v_pk_mul_f32 v[56:57], v[56:57], v[132:133]
	v_pk_mul_f32 v[52:53], v[52:53], v[136:137]
	v_pk_mul_f32 v[62:63], v[62:63], v[130:131]
	v_pk_mul_f32 v[58:59], v[58:59], v[134:135]
	v_pk_mul_f32 v[54:55], v[54:55], v[138:139]
	v_pk_mul_f32 v[50:51], v[50:51], v[142:143]
	v_pk_mul_f32 v[48:49], v[48:49], v[140:141]
	v_pk_mul_f32 v[44:45], v[44:45], v[128:129]
	v_pk_mul_f32 v[40:41], v[40:41], v[132:133]
	v_pk_mul_f32 v[36:37], v[36:37], v[136:137]
	v_pk_mul_f32 v[46:47], v[46:47], v[130:131]
	v_pk_mul_f32 v[42:43], v[42:43], v[134:135]
	v_pk_mul_f32 v[38:39], v[38:39], v[138:139]
	v_pk_mul_f32 v[34:35], v[34:35], v[142:143]
	v_pk_mul_f32 v[32:33], v[32:33], v[140:141]
	v_pk_mul_f32 v[28:29], v[28:29], v[128:129]
	v_pk_mul_f32 v[24:25], v[24:25], v[132:133]
	v_pk_mul_f32 v[20:21], v[20:21], v[136:137]
	v_pk_mul_f32 v[30:31], v[30:31], v[130:131]
	v_pk_mul_f32 v[26:27], v[26:27], v[134:135]
	v_pk_mul_f32 v[22:23], v[22:23], v[138:139]
	v_pk_mul_f32 v[18:19], v[18:19], v[142:143]
	v_pk_mul_f32 v[16:17], v[16:17], v[140:141]
